# G1 SEC1 (k_r) epilogue hand-rewritten: scalar RoPE rotation, decay factors hoisted, kdF/kdB 2-byte scatters replaced by LDS transpose + dwordx4 stores; plus earlier combined changes
# speedup vs baseline: 1.0092x; 1.0092x over previous
.LBB0_158:
	s_andn2_b64 vcc, exec, s[0:1]
	s_cbranch_vccnz .LBB0_166
	s_cmp_gt_i32 s2, 0
	s_mov_b64 s[0:1], -1
	s_cbranch_scc0 .LBB0_163
	s_lshl_b32 s1, s48, 8
	s_add_i32 s1, s1, s31
	v_add_u32_e32 v235, s1, v181
	v_lshlrev_b32_e32 v235, 2, v235
	global_load_dword v148, v235, s[70:71]
	global_load_dword v149, v235, s[70:71] offset:64
	global_load_dword v150, v235, s[70:71] offset:128
	global_load_dword v151, v235, s[70:71] offset:192
	global_load_dword v152, v235, s[70:71] offset:512
	global_load_dword v153, v235, s[70:71] offset:576
	global_load_dword v154, v235, s[70:71] offset:640
	global_load_dword v155, v235, s[70:71] offset:704
	s_add_i32 s3, s74, s49
	s_bfe_u32 s2, s3, 0x30006
	s_lshl_b32 s0, s2, 2
	v_mov_b32_e32 v236, s0
	global_load_dword v132, v236, s[80:81]
	global_load_dword v133, v236, s[80:81] offset:32
	s_and_b32 s42, s3, 63
	s_lshl_b32 s0, s31, 7
	s_lshl_b32 s44, s49, 6
	s_add_i32 s0, s0, s44
	s_add_i32 s0, s0, 0x20d40
	v_bfe_u32 v235, v213, 4, 2
	v_lshlrev_b32_e32 v236, 4, v235
	v_and_b32_e32 v134, 8, v181
	v_lshlrev_b32_e32 v134, 2, v134
	v_xor_b32_e32 v236, v236, v134
	v_lshl_add_u32 v168, v181, 6, v236
	v_add_u32_e32 v168, s0, v168
	v_bfe_u32 v236, v213, 2, 2
	v_lshl_add_u32 v236, v235, 3, v236
	v_lshlrev_b32_e32 v236, 6, v236
	v_and_b32_e32 v134, 1, v235
	v_lshl_add_u32 v236, v134, 5, v236
	v_and_b32_e32 v134, 3, v213
	v_lshl_add_u32 v236, v134, 3, v236
	v_add_u32_e32 v169, s0, v236
	v_xor_b32_e32 v236, 32, v236
	v_add_u32_e32 v220, s0, v236
	v_lshlrev_b32_e32 v223, 10, v181
	v_lshl_add_u32 v223, v235, 4, v223
	s_lshl_b32 s44, s42, 2
	v_lshl_add_u32 v234, v235, 5, s44
	v_lshl_add_u32 v234, v181, 8, v234
	v_add_u32_e32 v236, s42, v181
	v_mul_u32_u24_e32 v236, 0x1100, v236
	v_readlane_b32 s4, v251, 9
	v_readlane_b32 s5, v251, 10
	v_readlane_b32 s36, v251, 7
	v_readlane_b32 s37, v251, 8
	v_readlane_b32 s40, v251, 5
	v_readlane_b32 s41, v251, 6
	s_lshl_b32 s44, s3, 1
	s_add_u32 s16, s94, s44
	s_addc_u32 s17, s95, 0
	s_add_u32 s16, s16, 0x101fc00
	s_addc_u32 s17, s17, 0
	s_lshl_b32 s44, s1, 10
	s_add_u32 s16, s16, s44
	s_addc_u32 s17, s17, 0
	s_cmp_eq_u32 s48, 64
	s_cbranch_scc1 .Lsec1_a_meta
	v_lshl_add_u32 v221, v235, 4, v236
	v_add_u32_e32 v134, s31, v181
	s_lshr_b32 s44, s48, 3
	s_lshl_b32 s44, s44, 3
	s_add_i32 s44, s44, s2
	s_mul_i32 s44, s44, 0x44000
	s_and_b32 s45, s48, 7
	s_lshl_b32 s45, s45, 8
	s_add_i32 s45, s45, s31
	s_lshl_b32 s47, s45, 1
	s_add_i32 s44, s44, s47
	s_addk_i32 s44, 0x100
	s_add_i32 s45, s45, 16
	s_lshl_b32 s45, s45, 8
	s_movk_i32 s21, 0x1000
	s_mov_b32 s43, 64
	s_mov_b32 s3, 16
	s_branch .Lsec1_a_go
.Lsec1_a_meta:
	v_lshrrev_b32_e32 v134, 1, v235
	v_mul_u32_u24_e32 v134, 0x220000, v134
	v_and_b32_e32 v221, 1, v235
	v_lshl_add_u32 v221, v221, 4, v236
	v_add_u32_e32 v221, v221, v134
	v_add_u32_e32 v134, 0x70, v181
	s_mul_i32 s44, s2, 0x44000
	s_lshr_b32 s45, s31, 6
	s_mul_i32 s45, s45, 0x880000
	s_add_i32 s44, s44, s45
	s_addk_i32 s44, 0xe0
	s_mov_b32 s45, 0
	s_mov_b32 s21, 0
	s_mov_b32 s43, 0x440000
	s_mov_b32 s3, 0
.Lsec1_a_go:
	s_nop 3
	s_add_u32 s36, s36, s44
	s_addc_u32 s37, s37, 0
	s_add_u32 s40, s40, s44
	s_addc_u32 s41, s41, 0
	s_add_u32 s4, s4, s45
	s_addc_u32 s5, s5, 0
	v_add_u32_e32 v222, 0x11000, v221
	global_load_dwordx4 v[188:191], v234, s[4:5]
	global_load_dwordx4 v[192:195], v234, s[4:5] offset:16
	s_waitcnt vmcnt(2)
	v_mul_f32_e32 v132, 0x3fb8aa3b, v132
	v_exp_f32_e32 v132, v132
	v_mul_f32_e32 v133, 0x3fb8aa3b, v133
	v_exp_f32_e32 v133, v133
	v_sub_u32_e32 v156, 0x7f, v134
	v_cvt_f32_u32_e32 v156, v156
	v_mul_f32_e64 v156, v156, -v132
	v_mul_f32_e32 v156, 0x3fb8aa3b, v156
	v_exp_f32_e32 v156, v156
	v_cvt_f32_u32_e32 v160, v134
	v_mul_f32_e64 v160, v160, -v133
	v_mul_f32_e32 v160, 0x3fb8aa3b, v160
	v_exp_f32_e32 v160, v160
	v_add_u32_e32 v134, s3, v134
	v_sub_u32_e32 v157, 0x7f, v134
	v_cvt_f32_u32_e32 v157, v157
	v_mul_f32_e64 v157, v157, -v132
	v_mul_f32_e32 v157, 0x3fb8aa3b, v157
	v_exp_f32_e32 v157, v157
	v_cvt_f32_u32_e32 v161, v134
	v_mul_f32_e64 v161, v161, -v133
	v_mul_f32_e32 v161, 0x3fb8aa3b, v161
	v_exp_f32_e32 v161, v161
	v_add_u32_e32 v134, s3, v134
	v_sub_u32_e32 v158, 0x7f, v134
	v_cvt_f32_u32_e32 v158, v158
	v_mul_f32_e64 v158, v158, -v132
	v_mul_f32_e32 v158, 0x3fb8aa3b, v158
	v_exp_f32_e32 v158, v158
	v_cvt_f32_u32_e32 v162, v134
	v_mul_f32_e64 v162, v162, -v133
	v_mul_f32_e32 v162, 0x3fb8aa3b, v162
	v_exp_f32_e32 v162, v162
	v_add_u32_e32 v134, s3, v134
	v_sub_u32_e32 v159, 0x7f, v134
	v_cvt_f32_u32_e32 v159, v159
	v_mul_f32_e64 v159, v159, -v132
	v_mul_f32_e32 v159, 0x3fb8aa3b, v159
	v_exp_f32_e32 v159, v159
	v_cvt_f32_u32_e32 v163, v134
	v_mul_f32_e64 v163, v163, -v133
	v_mul_f32_e32 v163, 0x3fb8aa3b, v163
	v_exp_f32_e32 v163, v163
	s_add_u32 s4, s4, s21
	s_addc_u32 s5, s5, 0
	global_load_dwordx4 v[196:199], v234, s[4:5]
	global_load_dwordx4 v[200:203], v234, s[4:5] offset:16
	s_waitcnt vmcnt(2)
	v_mul_f32_e32 v132, v148, v128
	v_mul_f32_e32 v133, v148, v129
	v_mul_f32_e32 v134, v148, v130
	v_mul_f32_e32 v135, v148, v131
	v_mul_f32_e32 v136, v148, v124
	v_mul_f32_e32 v137, v148, v125
	v_mul_f32_e32 v138, v148, v126
	v_mul_f32_e32 v139, v148, v127
	v_mul_f32_e32 v235, v189, v133
	v_mul_f32_e32 v236, v189, v132
	v_fma_f32 v132, v188, v132, -v235
	v_fma_f32 v133, v188, v133, v236
	v_mul_f32_e32 v235, v191, v135
	v_mul_f32_e32 v236, v191, v134
	v_fma_f32 v134, v190, v134, -v235
	v_fma_f32 v135, v190, v135, v236
	v_mul_f32_e32 v235, v193, v137
	v_mul_f32_e32 v236, v193, v136
	v_fma_f32 v136, v192, v136, -v235
	v_fma_f32 v137, v192, v137, v236
	v_mul_f32_e32 v235, v195, v139
	v_mul_f32_e32 v236, v195, v138
	v_fma_f32 v138, v194, v138, -v235
	v_fma_f32 v139, v194, v139, v236
	v_cvt_pk_bf16_f32 v204, v132, v133
	v_cvt_pk_bf16_f32 v205, v134, v135
	v_cvt_pk_bf16_f32 v206, v136, v137
	v_cvt_pk_bf16_f32 v207, v138, v139
	global_store_dwordx4 v223, v[204:207], s[16:17]
	s_add_u32 s16, s16, 0x4000
	s_addc_u32 s17, s17, 0
	v_mul_f32_e32 v235, v156, v132
	v_mul_f32_e32 v236, v156, v133
	v_cvt_pk_bf16_f32 v208, v235, v236
	v_mul_f32_e32 v235, v156, v134
	v_mul_f32_e32 v236, v156, v135
	v_cvt_pk_bf16_f32 v209, v235, v236
	v_mul_f32_e32 v235, v156, v136
	v_mul_f32_e32 v236, v156, v137
	v_cvt_pk_bf16_f32 v210, v235, v236
	v_mul_f32_e32 v235, v156, v138
	v_mul_f32_e32 v236, v156, v139
	v_cvt_pk_bf16_f32 v211, v235, v236
	ds_write_b128 v168, v[208:211]
	v_mul_f32_e32 v235, v160, v132
	v_mul_f32_e32 v236, v160, v133
	v_cvt_pk_bf16_f32 v140, v235, v236
	v_mul_f32_e32 v235, v160, v134
	v_mul_f32_e32 v236, v160, v135
	v_cvt_pk_bf16_f32 v141, v235, v236
	v_mul_f32_e32 v235, v160, v136
	v_mul_f32_e32 v236, v160, v137
	v_cvt_pk_bf16_f32 v142, v235, v236
	v_mul_f32_e32 v235, v160, v138
	v_mul_f32_e32 v236, v160, v139
	v_cvt_pk_bf16_f32 v143, v235, v236
	s_add_u32 s4, s4, s21
	s_addc_u32 s5, s5, 0
	global_load_dwordx4 v[188:191], v234, s[4:5]
	global_load_dwordx4 v[192:195], v234, s[4:5] offset:16
	s_waitcnt vmcnt(2)
	v_mul_f32_e32 v132, v149, v120
	v_mul_f32_e32 v133, v149, v121
	v_mul_f32_e32 v134, v149, v122
	v_mul_f32_e32 v135, v149, v123
	v_mul_f32_e32 v136, v149, v116
	v_mul_f32_e32 v137, v149, v117
	v_mul_f32_e32 v138, v149, v118
	v_mul_f32_e32 v139, v149, v119
	v_mul_f32_e32 v235, v197, v133
	v_mul_f32_e32 v236, v197, v132
	v_fma_f32 v132, v196, v132, -v235
	v_fma_f32 v133, v196, v133, v236
	v_mul_f32_e32 v235, v199, v135
	v_mul_f32_e32 v236, v199, v134
	v_fma_f32 v134, v198, v134, -v235
	v_fma_f32 v135, v198, v135, v236
	v_mul_f32_e32 v235, v201, v137
	v_mul_f32_e32 v236, v201, v136
	v_fma_f32 v136, v200, v136, -v235
	v_fma_f32 v137, v200, v137, v236
	v_mul_f32_e32 v235, v203, v139
	v_mul_f32_e32 v236, v203, v138
	v_fma_f32 v138, v202, v138, -v235
	v_fma_f32 v139, v202, v139, v236
	v_cvt_pk_bf16_f32 v204, v132, v133
	v_cvt_pk_bf16_f32 v205, v134, v135
	v_cvt_pk_bf16_f32 v206, v136, v137
	v_cvt_pk_bf16_f32 v207, v138, v139
	global_store_dwordx4 v223, v[204:207], s[16:17]
	s_add_u32 s16, s16, 0x4000
	s_addc_u32 s17, s17, 0
	v_mul_f32_e32 v235, v157, v132
	v_mul_f32_e32 v236, v157, v133
	v_cvt_pk_bf16_f32 v208, v235, v236
	v_mul_f32_e32 v235, v157, v134
	v_mul_f32_e32 v236, v157, v135
	v_cvt_pk_bf16_f32 v209, v235, v236
	v_mul_f32_e32 v235, v157, v136
	v_mul_f32_e32 v236, v157, v137
	v_cvt_pk_bf16_f32 v210, v235, v236
	v_mul_f32_e32 v235, v157, v138
	v_mul_f32_e32 v236, v157, v139
	v_cvt_pk_bf16_f32 v211, v235, v236
	ds_write_b128 v168, v[208:211] offset:1024
	v_mul_f32_e32 v235, v161, v132
	v_mul_f32_e32 v236, v161, v133
	v_cvt_pk_bf16_f32 v144, v235, v236
	v_mul_f32_e32 v235, v161, v134
	v_mul_f32_e32 v236, v161, v135
	v_cvt_pk_bf16_f32 v145, v235, v236
	v_mul_f32_e32 v235, v161, v136
	v_mul_f32_e32 v236, v161, v137
	v_cvt_pk_bf16_f32 v146, v235, v236
	v_mul_f32_e32 v235, v161, v138
	v_mul_f32_e32 v236, v161, v139
	v_cvt_pk_bf16_f32 v147, v235, v236
	ds_read_b64_tr_b16 v[204:205], v169
	ds_read_b64_tr_b16 v[206:207], v169 offset:256
	ds_read_b64_tr_b16 v[208:209], v220
	ds_read_b64_tr_b16 v[210:211], v220 offset:256
	s_waitcnt lgkmcnt(0)
	global_store_dwordx4 v221, v[204:207], s[36:37]
	global_store_dwordx4 v222, v[208:211], s[36:37]
	ds_write_b128 v168, v[140:143]
	ds_write_b128 v168, v[144:147] offset:1024
	s_nop 1
	ds_read_b64_tr_b16 v[204:205], v169
	ds_read_b64_tr_b16 v[206:207], v169 offset:256
	ds_read_b64_tr_b16 v[208:209], v220
	ds_read_b64_tr_b16 v[210:211], v220 offset:256
	s_waitcnt lgkmcnt(0)
	global_store_dwordx4 v221, v[204:207], s[40:41]
	global_store_dwordx4 v222, v[208:211], s[40:41]
	s_add_u32 s36, s36, s43
	s_addc_u32 s37, s37, 0
	s_add_u32 s40, s40, s43
	s_addc_u32 s41, s41, 0
	s_add_u32 s4, s4, s21
	s_addc_u32 s5, s5, 0
	global_load_dwordx4 v[196:199], v234, s[4:5]
	global_load_dwordx4 v[200:203], v234, s[4:5] offset:16
	s_waitcnt vmcnt(2)
	v_mul_f32_e32 v132, v150, v112
	v_mul_f32_e32 v133, v150, v113
	v_mul_f32_e32 v134, v150, v114
	v_mul_f32_e32 v135, v150, v115
	v_mul_f32_e32 v136, v150, v108
	v_mul_f32_e32 v137, v150, v109
	v_mul_f32_e32 v138, v150, v110
	v_mul_f32_e32 v139, v150, v111
	v_mul_f32_e32 v235, v189, v133
	v_mul_f32_e32 v236, v189, v132
	v_fma_f32 v132, v188, v132, -v235
	v_fma_f32 v133, v188, v133, v236
	v_mul_f32_e32 v235, v191, v135
	v_mul_f32_e32 v236, v191, v134
	v_fma_f32 v134, v190, v134, -v235
	v_fma_f32 v135, v190, v135, v236
	v_mul_f32_e32 v235, v193, v137
	v_mul_f32_e32 v236, v193, v136
	v_fma_f32 v136, v192, v136, -v235
	v_fma_f32 v137, v192, v137, v236
	v_mul_f32_e32 v235, v195, v139
	v_mul_f32_e32 v236, v195, v138
	v_fma_f32 v138, v194, v138, -v235
	v_fma_f32 v139, v194, v139, v236
	v_cvt_pk_bf16_f32 v204, v132, v133
	v_cvt_pk_bf16_f32 v205, v134, v135
	v_cvt_pk_bf16_f32 v206, v136, v137
	v_cvt_pk_bf16_f32 v207, v138, v139
	global_store_dwordx4 v223, v[204:207], s[16:17]
	s_add_u32 s16, s16, 0x4000
	s_addc_u32 s17, s17, 0
	v_mul_f32_e32 v235, v158, v132
	v_mul_f32_e32 v236, v158, v133
	v_cvt_pk_bf16_f32 v208, v235, v236
	v_mul_f32_e32 v235, v158, v134
	v_mul_f32_e32 v236, v158, v135
	v_cvt_pk_bf16_f32 v209, v235, v236
	v_mul_f32_e32 v235, v158, v136
	v_mul_f32_e32 v236, v158, v137
	v_cvt_pk_bf16_f32 v210, v235, v236
	v_mul_f32_e32 v235, v158, v138
	v_mul_f32_e32 v236, v158, v139
	v_cvt_pk_bf16_f32 v211, v235, v236
	ds_write_b128 v168, v[208:211]
	v_mul_f32_e32 v235, v162, v132
	v_mul_f32_e32 v236, v162, v133
	v_cvt_pk_bf16_f32 v140, v235, v236
	v_mul_f32_e32 v235, v162, v134
	v_mul_f32_e32 v236, v162, v135
	v_cvt_pk_bf16_f32 v141, v235, v236
	v_mul_f32_e32 v235, v162, v136
	v_mul_f32_e32 v236, v162, v137
	v_cvt_pk_bf16_f32 v142, v235, v236
	v_mul_f32_e32 v235, v162, v138
	v_mul_f32_e32 v236, v162, v139
	v_cvt_pk_bf16_f32 v143, v235, v236
	s_add_u32 s4, s4, 0x5000
	s_addc_u32 s5, s5, 0
	global_load_dwordx4 v[188:191], v234, s[4:5]
	global_load_dwordx4 v[192:195], v234, s[4:5] offset:16
	s_waitcnt vmcnt(2)
	v_mul_f32_e32 v132, v151, v104
	v_mul_f32_e32 v133, v151, v105
	v_mul_f32_e32 v134, v151, v106
	v_mul_f32_e32 v135, v151, v107
	v_mul_f32_e32 v136, v151, v100
	v_mul_f32_e32 v137, v151, v101
	v_mul_f32_e32 v138, v151, v102
	v_mul_f32_e32 v139, v151, v103
	v_mul_f32_e32 v235, v197, v133
	v_mul_f32_e32 v236, v197, v132
	v_fma_f32 v132, v196, v132, -v235
	v_fma_f32 v133, v196, v133, v236
	v_mul_f32_e32 v235, v199, v135
	v_mul_f32_e32 v236, v199, v134
	v_fma_f32 v134, v198, v134, -v235
	v_fma_f32 v135, v198, v135, v236
	v_mul_f32_e32 v235, v201, v137
	v_mul_f32_e32 v236, v201, v136
	v_fma_f32 v136, v200, v136, -v235
	v_fma_f32 v137, v200, v137, v236
	v_mul_f32_e32 v235, v203, v139
	v_mul_f32_e32 v236, v203, v138
	v_fma_f32 v138, v202, v138, -v235
	v_fma_f32 v139, v202, v139, v236
	v_cvt_pk_bf16_f32 v204, v132, v133
	v_cvt_pk_bf16_f32 v205, v134, v135
	v_cvt_pk_bf16_f32 v206, v136, v137
	v_cvt_pk_bf16_f32 v207, v138, v139
	global_store_dwordx4 v223, v[204:207], s[16:17]
	s_add_u32 s16, s16, 0x14000
	s_addc_u32 s17, s17, 0
	v_mul_f32_e32 v235, v159, v132
	v_mul_f32_e32 v236, v159, v133
	v_cvt_pk_bf16_f32 v208, v235, v236
	v_mul_f32_e32 v235, v159, v134
	v_mul_f32_e32 v236, v159, v135
	v_cvt_pk_bf16_f32 v209, v235, v236
	v_mul_f32_e32 v235, v159, v136
	v_mul_f32_e32 v236, v159, v137
	v_cvt_pk_bf16_f32 v210, v235, v236
	v_mul_f32_e32 v235, v159, v138
	v_mul_f32_e32 v236, v159, v139
	v_cvt_pk_bf16_f32 v211, v235, v236
	ds_write_b128 v168, v[208:211] offset:1024
	v_mul_f32_e32 v235, v163, v132
	v_mul_f32_e32 v236, v163, v133
	v_cvt_pk_bf16_f32 v144, v235, v236
	v_mul_f32_e32 v235, v163, v134
	v_mul_f32_e32 v236, v163, v135
	v_cvt_pk_bf16_f32 v145, v235, v236
	v_mul_f32_e32 v235, v163, v136
	v_mul_f32_e32 v236, v163, v137
	v_cvt_pk_bf16_f32 v146, v235, v236
	v_mul_f32_e32 v235, v163, v138
	v_mul_f32_e32 v236, v163, v139
	v_cvt_pk_bf16_f32 v147, v235, v236
	ds_read_b64_tr_b16 v[204:205], v169
	ds_read_b64_tr_b16 v[206:207], v169 offset:256
	ds_read_b64_tr_b16 v[208:209], v220
	ds_read_b64_tr_b16 v[210:211], v220 offset:256
	s_waitcnt lgkmcnt(0)
	global_store_dwordx4 v221, v[204:207], s[36:37]
	global_store_dwordx4 v222, v[208:211], s[36:37]
	ds_write_b128 v168, v[140:143]
	ds_write_b128 v168, v[144:147] offset:1024
	s_nop 1
	ds_read_b64_tr_b16 v[204:205], v169
	ds_read_b64_tr_b16 v[206:207], v169 offset:256
	ds_read_b64_tr_b16 v[208:209], v220
	ds_read_b64_tr_b16 v[210:211], v220 offset:256
	s_waitcnt lgkmcnt(0)
	global_store_dwordx4 v221, v[204:207], s[40:41]
	global_store_dwordx4 v222, v[208:211], s[40:41]
	s_add_u32 s36, s36, 0xc0
	s_addc_u32 s37, s37, 0
	s_add_u32 s40, s40, 0xc0
	s_addc_u32 s41, s41, 0
	s_cmp_eq_u32 s48, 64
	s_cbranch_scc1 .Lsec1_a_done
	s_add_u32 s4, s4, s21
	s_addc_u32 s5, s5, 0
	global_load_dwordx4 v[196:199], v234, s[4:5]
	global_load_dwordx4 v[200:203], v234, s[4:5] offset:16
	s_waitcnt vmcnt(2)
	v_mul_f32_e32 v132, v152, v96
	v_mul_f32_e32 v133, v152, v97
	v_mul_f32_e32 v134, v152, v98
	v_mul_f32_e32 v135, v152, v99
	v_mul_f32_e32 v136, v152, v92
	v_mul_f32_e32 v137, v152, v93
	v_mul_f32_e32 v138, v152, v94
	v_mul_f32_e32 v139, v152, v95
	v_mul_f32_e32 v235, v189, v133
	v_mul_f32_e32 v236, v189, v132
	v_fma_f32 v132, v188, v132, -v235
	v_fma_f32 v133, v188, v133, v236
	v_mul_f32_e32 v235, v191, v135
	v_mul_f32_e32 v236, v191, v134
	v_fma_f32 v134, v190, v134, -v235
	v_fma_f32 v135, v190, v135, v236
	v_mul_f32_e32 v235, v193, v137
	v_mul_f32_e32 v236, v193, v136
	v_fma_f32 v136, v192, v136, -v235
	v_fma_f32 v137, v192, v137, v236
	v_mul_f32_e32 v235, v195, v139
	v_mul_f32_e32 v236, v195, v138
	v_fma_f32 v138, v194, v138, -v235
	v_fma_f32 v139, v194, v139, v236
	v_cvt_pk_bf16_f32 v204, v132, v133
	v_cvt_pk_bf16_f32 v205, v134, v135
	v_cvt_pk_bf16_f32 v206, v136, v137
	v_cvt_pk_bf16_f32 v207, v138, v139
	global_store_dwordx4 v223, v[204:207], s[16:17]
	s_add_u32 s16, s16, 0x4000
	s_addc_u32 s17, s17, 0
	v_mul_f32_e32 v235, v156, v132
	v_mul_f32_e32 v236, v156, v133
	v_cvt_pk_bf16_f32 v208, v235, v236
	v_mul_f32_e32 v235, v156, v134
	v_mul_f32_e32 v236, v156, v135
	v_cvt_pk_bf16_f32 v209, v235, v236
	v_mul_f32_e32 v235, v156, v136
	v_mul_f32_e32 v236, v156, v137
	v_cvt_pk_bf16_f32 v210, v235, v236
	v_mul_f32_e32 v235, v156, v138
	v_mul_f32_e32 v236, v156, v139
	v_cvt_pk_bf16_f32 v211, v235, v236
	ds_write_b128 v168, v[208:211]
	v_mul_f32_e32 v235, v160, v132
	v_mul_f32_e32 v236, v160, v133
	v_cvt_pk_bf16_f32 v140, v235, v236
	v_mul_f32_e32 v235, v160, v134
	v_mul_f32_e32 v236, v160, v135
	v_cvt_pk_bf16_f32 v141, v235, v236
	v_mul_f32_e32 v235, v160, v136
	v_mul_f32_e32 v236, v160, v137
	v_cvt_pk_bf16_f32 v142, v235, v236
	v_mul_f32_e32 v235, v160, v138
	v_mul_f32_e32 v236, v160, v139
	v_cvt_pk_bf16_f32 v143, v235, v236
	s_add_u32 s4, s4, s21
	s_addc_u32 s5, s5, 0
	global_load_dwordx4 v[188:191], v234, s[4:5]
	global_load_dwordx4 v[192:195], v234, s[4:5] offset:16
	s_waitcnt vmcnt(2)
	v_mul_f32_e32 v132, v153, v88
	v_mul_f32_e32 v133, v153, v89
	v_mul_f32_e32 v134, v153, v90
	v_mul_f32_e32 v135, v153, v91
	v_mul_f32_e32 v136, v153, v84
	v_mul_f32_e32 v137, v153, v85
	v_mul_f32_e32 v138, v153, v86
	v_mul_f32_e32 v139, v153, v87
	v_mul_f32_e32 v235, v197, v133
	v_mul_f32_e32 v236, v197, v132
	v_fma_f32 v132, v196, v132, -v235
	v_fma_f32 v133, v196, v133, v236
	v_mul_f32_e32 v235, v199, v135
	v_mul_f32_e32 v236, v199, v134
	v_fma_f32 v134, v198, v134, -v235
	v_fma_f32 v135, v198, v135, v236
	v_mul_f32_e32 v235, v201, v137
	v_mul_f32_e32 v236, v201, v136
	v_fma_f32 v136, v200, v136, -v235
	v_fma_f32 v137, v200, v137, v236
	v_mul_f32_e32 v235, v203, v139
	v_mul_f32_e32 v236, v203, v138
	v_fma_f32 v138, v202, v138, -v235
	v_fma_f32 v139, v202, v139, v236
	v_cvt_pk_bf16_f32 v204, v132, v133
	v_cvt_pk_bf16_f32 v205, v134, v135
	v_cvt_pk_bf16_f32 v206, v136, v137
	v_cvt_pk_bf16_f32 v207, v138, v139
	global_store_dwordx4 v223, v[204:207], s[16:17]
	s_add_u32 s16, s16, 0x4000
	s_addc_u32 s17, s17, 0
	v_mul_f32_e32 v235, v157, v132
	v_mul_f32_e32 v236, v157, v133
	v_cvt_pk_bf16_f32 v208, v235, v236
	v_mul_f32_e32 v235, v157, v134
	v_mul_f32_e32 v236, v157, v135
	v_cvt_pk_bf16_f32 v209, v235, v236
	v_mul_f32_e32 v235, v157, v136
	v_mul_f32_e32 v236, v157, v137
	v_cvt_pk_bf16_f32 v210, v235, v236
	v_mul_f32_e32 v235, v157, v138
	v_mul_f32_e32 v236, v157, v139
	v_cvt_pk_bf16_f32 v211, v235, v236
	ds_write_b128 v168, v[208:211] offset:1024
	v_mul_f32_e32 v235, v161, v132
	v_mul_f32_e32 v236, v161, v133
	v_cvt_pk_bf16_f32 v144, v235, v236
	v_mul_f32_e32 v235, v161, v134
	v_mul_f32_e32 v236, v161, v135
	v_cvt_pk_bf16_f32 v145, v235, v236
	v_mul_f32_e32 v235, v161, v136
	v_mul_f32_e32 v236, v161, v137
	v_cvt_pk_bf16_f32 v146, v235, v236
	v_mul_f32_e32 v235, v161, v138
	v_mul_f32_e32 v236, v161, v139
	v_cvt_pk_bf16_f32 v147, v235, v236
	ds_read_b64_tr_b16 v[204:205], v169
	ds_read_b64_tr_b16 v[206:207], v169 offset:256
	ds_read_b64_tr_b16 v[208:209], v220
	ds_read_b64_tr_b16 v[210:211], v220 offset:256
	s_waitcnt lgkmcnt(0)
	global_store_dwordx4 v221, v[204:207], s[36:37]
	global_store_dwordx4 v222, v[208:211], s[36:37]
	ds_write_b128 v168, v[140:143]
	ds_write_b128 v168, v[144:147] offset:1024
	s_nop 1
	ds_read_b64_tr_b16 v[204:205], v169
	ds_read_b64_tr_b16 v[206:207], v169 offset:256
	ds_read_b64_tr_b16 v[208:209], v220
	ds_read_b64_tr_b16 v[210:211], v220 offset:256
	s_waitcnt lgkmcnt(0)
	global_store_dwordx4 v221, v[204:207], s[40:41]
	global_store_dwordx4 v222, v[208:211], s[40:41]
	s_add_u32 s36, s36, 64
	s_addc_u32 s37, s37, 0
	s_add_u32 s40, s40, 64
	s_addc_u32 s41, s41, 0
	s_add_u32 s4, s4, s21
	s_addc_u32 s5, s5, 0
	global_load_dwordx4 v[196:199], v234, s[4:5]
	global_load_dwordx4 v[200:203], v234, s[4:5] offset:16
	s_waitcnt vmcnt(2)
	v_mul_f32_e32 v132, v154, v80
	v_mul_f32_e32 v133, v154, v81
	v_mul_f32_e32 v134, v154, v82
	v_mul_f32_e32 v135, v154, v83
	v_mul_f32_e32 v136, v154, v76
	v_mul_f32_e32 v137, v154, v77
	v_mul_f32_e32 v138, v154, v78
	v_mul_f32_e32 v139, v154, v79
	v_mul_f32_e32 v235, v189, v133
	v_mul_f32_e32 v236, v189, v132
	v_fma_f32 v132, v188, v132, -v235
	v_fma_f32 v133, v188, v133, v236
	v_mul_f32_e32 v235, v191, v135
	v_mul_f32_e32 v236, v191, v134
	v_fma_f32 v134, v190, v134, -v235
	v_fma_f32 v135, v190, v135, v236
	v_mul_f32_e32 v235, v193, v137
	v_mul_f32_e32 v236, v193, v136
	v_fma_f32 v136, v192, v136, -v235
	v_fma_f32 v137, v192, v137, v236
	v_mul_f32_e32 v235, v195, v139
	v_mul_f32_e32 v236, v195, v138
	v_fma_f32 v138, v194, v138, -v235
	v_fma_f32 v139, v194, v139, v236
	v_cvt_pk_bf16_f32 v204, v132, v133
	v_cvt_pk_bf16_f32 v205, v134, v135
	v_cvt_pk_bf16_f32 v206, v136, v137
	v_cvt_pk_bf16_f32 v207, v138, v139
	global_store_dwordx4 v223, v[204:207], s[16:17]
	s_add_u32 s16, s16, 0x4000
	s_addc_u32 s17, s17, 0
	v_mul_f32_e32 v235, v158, v132
	v_mul_f32_e32 v236, v158, v133
	v_cvt_pk_bf16_f32 v208, v235, v236
	v_mul_f32_e32 v235, v158, v134
	v_mul_f32_e32 v236, v158, v135
	v_cvt_pk_bf16_f32 v209, v235, v236
	v_mul_f32_e32 v235, v158, v136
	v_mul_f32_e32 v236, v158, v137
	v_cvt_pk_bf16_f32 v210, v235, v236
	v_mul_f32_e32 v235, v158, v138
	v_mul_f32_e32 v236, v158, v139
	v_cvt_pk_bf16_f32 v211, v235, v236
	ds_write_b128 v168, v[208:211]
	v_mul_f32_e32 v235, v162, v132
	v_mul_f32_e32 v236, v162, v133
	v_cvt_pk_bf16_f32 v140, v235, v236
	v_mul_f32_e32 v235, v162, v134
	v_mul_f32_e32 v236, v162, v135
	v_cvt_pk_bf16_f32 v141, v235, v236
	v_mul_f32_e32 v235, v162, v136
	v_mul_f32_e32 v236, v162, v137
	v_cvt_pk_bf16_f32 v142, v235, v236
	v_mul_f32_e32 v235, v162, v138
	v_mul_f32_e32 v236, v162, v139
	v_cvt_pk_bf16_f32 v143, v235, v236
	s_waitcnt vmcnt(0)
	v_mul_f32_e32 v132, v155, v72
	v_mul_f32_e32 v133, v155, v73
	v_mul_f32_e32 v134, v155, v74
	v_mul_f32_e32 v135, v155, v75
	v_mul_f32_e32 v136, v155, v68
	v_mul_f32_e32 v137, v155, v69
	v_mul_f32_e32 v138, v155, v70
	v_mul_f32_e32 v139, v155, v71
	v_mul_f32_e32 v235, v197, v133
	v_mul_f32_e32 v236, v197, v132
	v_fma_f32 v132, v196, v132, -v235
	v_fma_f32 v133, v196, v133, v236
	v_mul_f32_e32 v235, v199, v135
	v_mul_f32_e32 v236, v199, v134
	v_fma_f32 v134, v198, v134, -v235
	v_fma_f32 v135, v198, v135, v236
	v_mul_f32_e32 v235, v201, v137
	v_mul_f32_e32 v236, v201, v136
	v_fma_f32 v136, v200, v136, -v235
	v_fma_f32 v137, v200, v137, v236
	v_mul_f32_e32 v235, v203, v139
	v_mul_f32_e32 v236, v203, v138
	v_fma_f32 v138, v202, v138, -v235
	v_fma_f32 v139, v202, v139, v236
	v_cvt_pk_bf16_f32 v204, v132, v133
	v_cvt_pk_bf16_f32 v205, v134, v135
	v_cvt_pk_bf16_f32 v206, v136, v137
	v_cvt_pk_bf16_f32 v207, v138, v139
	global_store_dwordx4 v223, v[204:207], s[16:17]
	s_add_u32 s16, s16, 0x14000
	s_addc_u32 s17, s17, 0
	v_mul_f32_e32 v235, v159, v132
	v_mul_f32_e32 v236, v159, v133
	v_cvt_pk_bf16_f32 v208, v235, v236
	v_mul_f32_e32 v235, v159, v134
	v_mul_f32_e32 v236, v159, v135
	v_cvt_pk_bf16_f32 v209, v235, v236
	v_mul_f32_e32 v235, v159, v136
	v_mul_f32_e32 v236, v159, v137
	v_cvt_pk_bf16_f32 v210, v235, v236
	v_mul_f32_e32 v235, v159, v138
	v_mul_f32_e32 v236, v159, v139
	v_cvt_pk_bf16_f32 v211, v235, v236
	ds_write_b128 v168, v[208:211] offset:1024
	v_mul_f32_e32 v235, v163, v132
	v_mul_f32_e32 v236, v163, v133
	v_cvt_pk_bf16_f32 v144, v235, v236
	v_mul_f32_e32 v235, v163, v134
	v_mul_f32_e32 v236, v163, v135
	v_cvt_pk_bf16_f32 v145, v235, v236
	v_mul_f32_e32 v235, v163, v136
	v_mul_f32_e32 v236, v163, v137
	v_cvt_pk_bf16_f32 v146, v235, v236
	v_mul_f32_e32 v235, v163, v138
	v_mul_f32_e32 v236, v163, v139
	v_cvt_pk_bf16_f32 v147, v235, v236
	ds_read_b64_tr_b16 v[204:205], v169
	ds_read_b64_tr_b16 v[206:207], v169 offset:256
	ds_read_b64_tr_b16 v[208:209], v220
	ds_read_b64_tr_b16 v[210:211], v220 offset:256
	s_waitcnt lgkmcnt(0)
	global_store_dwordx4 v221, v[204:207], s[36:37]
	global_store_dwordx4 v222, v[208:211], s[36:37]
	ds_write_b128 v168, v[140:143]
	ds_write_b128 v168, v[144:147] offset:1024
	s_nop 1
	ds_read_b64_tr_b16 v[204:205], v169
	ds_read_b64_tr_b16 v[206:207], v169 offset:256
	ds_read_b64_tr_b16 v[208:209], v220
	ds_read_b64_tr_b16 v[210:211], v220 offset:256
	s_waitcnt lgkmcnt(0)
	global_store_dwordx4 v221, v[204:207], s[40:41]
	global_store_dwordx4 v222, v[208:211], s[40:41]
.Lsec1_a_done:
.LBB0_162:
	s_mov_b64 s[0:1], 0
.LBB0_163:
	s_andn2_b64 vcc, exec, s[0:1]
	s_cbranch_vccnz .LBB0_166
	s_lshl_b32 s0, s48, 8
	v_add_u32_e32 v156, s0, v241
	s_movk_i32 s0, 0x7cf
	v_cmp_gt_i32_e32 vcc, s20, v156
	v_and_or_b32 v2, v156, s0, 16
	v_ashrrev_i32_e32 v157, 31, v156
	v_cndmask_b32_e32 v2, v181, v2, vcc
	v_lshl_add_u64 v[140:141], v[156:157], 2, s[70:71]
	v_lshlrev_b32_e32 v2, 8, v2
	global_load_dword v204, v[140:141], off
	v_lshl_add_u64 v[132:133], v[182:183], 0, v[2:3]
	global_load_dwordx4 v[196:199], v[132:133], off offset:16
	global_load_dwordx4 v[200:203], v[132:133], off
	s_movk_i32 s0, 0x7df
	v_or_b32_e32 v158, 16, v156
	v_bitop3_b32 v2, v156, s0, 16 bitop3:0xc8
	v_cmp_gt_i32_e32 vcc, s20, v158
	v_add_u32_e32 v2, 16, v2
	global_load_dword v188, v[140:141], off offset:64
	v_cndmask_b32_e32 v2, v181, v2, vcc
	v_lshlrev_b32_e32 v2, 8, v2
	v_lshl_add_u64 v[132:133], v[182:183], 0, v[2:3]
	global_load_dwordx4 v[144:147], v[132:133], off offset:16
	global_load_dwordx4 v[152:155], v[132:133], off
	v_or_b32_e32 v160, 32, v156
	s_movk_i32 s0, 0x7ef
	v_cmp_gt_i32_e32 vcc, s20, v160
	v_and_or_b32 v2, v160, s0, 16
	global_load_dword v190, v[140:141], off offset:128
	v_cndmask_b32_e32 v2, v181, v2, vcc
	v_lshlrev_b32_e32 v2, 8, v2
	v_lshl_add_u64 v[136:137], v[182:183], 0, v[2:3]
	global_load_dwordx4 v[132:135], v[136:137], off offset:16
	s_nop 0
	global_load_dwordx4 v[136:139], v[136:137], off
	s_movk_i32 s0, 0x7ff
	v_or_b32_e32 v162, 48, v156
	v_bitop3_b32 v2, v156, s0, 48 bitop3:0xc8
	v_cmp_gt_i32_e32 vcc, s20, v162
	v_add_u32_e32 v2, 16, v2
	global_load_dword v192, v[140:141], off offset:192
	v_cndmask_b32_e32 v2, v181, v2, vcc
	v_lshlrev_b32_e32 v2, 8, v2
	v_lshl_add_u64 v[148:149], v[182:183], 0, v[2:3]
	global_load_dwordx4 v[140:143], v[148:149], off offset:16
	s_nop 0
	global_load_dwordx4 v[148:151], v[148:149], off
	v_or_b32_e32 v194, s74, v178
	v_ashrrev_i32_e32 v195, 31, v194
	s_mov_b32 s0, 0x3e000000
	v_ashrrev_i32_e32 v159, 31, v158
	v_ashrrev_i32_e32 v161, 31, v160
	v_ashrrev_i32_e32 v163, 31, v162
	s_cmp_eq_u32 s48, 64
	s_waitcnt vmcnt(0)
	v_pk_mul_f32 v[128:129], v[128:129], v[204:205] op_sel_hi:[1,0]
	v_pk_mul_f32 v[130:131], v[130:131], v[204:205] op_sel_hi:[1,0]
	v_pk_mul_f32 v[206:207], v[200:201], v[128:129] op_sel:[1,1] op_sel_hi:[1,0]
	v_mov_b32_e32 v2, v203
	v_pk_fma_f32 v[208:209], v[200:201], v[128:129], v[206:207] op_sel_hi:[0,1,1] neg_lo:[0,0,1] neg_hi:[0,0,1]
	v_pk_fma_f32 v[128:129], v[200:201], v[128:129], v[206:207] op_sel_hi:[0,1,1]
	v_pk_mul_f32 v[200:201], v[2:3], v[130:131] op_sel:[0,1] op_sel_hi:[0,0]
	v_pk_mul_f32 v[124:125], v[124:125], v[204:205] op_sel_hi:[1,0]
	v_pk_fma_f32 v[206:207], v[202:203], v[130:131], v[200:201] op_sel_hi:[0,1,1] neg_lo:[0,0,1] neg_hi:[0,0,1]
	v_pk_fma_f32 v[130:131], v[202:203], v[130:131], v[200:201] op_sel_hi:[0,1,1]
	v_pk_mul_f32 v[126:127], v[126:127], v[204:205] op_sel_hi:[1,0]
	v_pk_mul_f32 v[200:201], v[196:197], v[124:125] op_sel:[1,1] op_sel_hi:[1,0]
	v_mov_b32_e32 v2, v199
	v_pk_fma_f32 v[202:203], v[196:197], v[124:125], v[200:201] op_sel_hi:[0,1,1] neg_lo:[0,0,1] neg_hi:[0,0,1]
	v_pk_fma_f32 v[124:125], v[196:197], v[124:125], v[200:201] op_sel_hi:[0,1,1]
	v_pk_mul_f32 v[196:197], v[2:3], v[126:127] op_sel:[0,1] op_sel_hi:[0,0]
	v_pk_fma_f32 v[200:201], v[198:199], v[126:127], v[196:197] op_sel_hi:[0,1,1] neg_lo:[0,0,1] neg_hi:[0,0,1]
	v_pk_fma_f32 v[126:127], v[198:199], v[126:127], v[196:197] op_sel_hi:[0,1,1]
	v_mov_b32_e32 v207, v131
	v_mov_b32_e32 v209, v129
	v_mov_b32_e32 v201, v127
	v_mov_b32_e32 v203, v125
	v_lshlrev_b64 v[124:125], 10, v[156:157]
	v_pk_mul_f32 v[130:131], v[206:207], s[0:1] op_sel_hi:[1,0]
	v_pk_mul_f32 v[128:129], v[208:209], s[0:1] op_sel_hi:[1,0]
	v_pk_mul_f32 v[196:197], v[200:201], s[0:1] op_sel_hi:[1,0]
	v_pk_mul_f32 v[198:199], v[202:203], s[0:1] op_sel_hi:[1,0]
	v_lshl_add_u64 v[126:127], s[94:95], 0, v[124:125]
	v_lshlrev_b64 v[124:125], 1, v[194:195]
	v_lshl_add_u64 v[194:195], v[126:127], 0, v[124:125]
	v_cvt_pk_bf16_f32 v126, v128, v129
	v_cvt_pk_bf16_f32 v127, v130, v131
	v_cvt_pk_bf16_f32 v128, v198, v199
	v_cvt_pk_bf16_f32 v129, v196, v197
	v_pk_mul_f32 v[120:121], v[120:121], v[188:189] op_sel_hi:[1,0]
	global_store_dwordx4 v[194:195], v[126:129], off
	v_pk_mul_f32 v[122:123], v[122:123], v[188:189] op_sel_hi:[1,0]
	v_mov_b32_e32 v2, v155
	v_pk_mul_f32 v[126:127], v[152:153], v[120:121] op_sel:[1,1] op_sel_hi:[1,0]
	v_pk_mul_f32 v[116:117], v[116:117], v[188:189] op_sel_hi:[1,0]
	v_pk_fma_f32 v[128:129], v[152:153], v[120:121], v[126:127] op_sel_hi:[0,1,1] neg_lo:[0,0,1] neg_hi:[0,0,1]
	v_pk_fma_f32 v[120:121], v[152:153], v[120:121], v[126:127] op_sel_hi:[0,1,1]
	v_pk_mul_f32 v[126:127], v[2:3], v[122:123] op_sel:[0,1] op_sel_hi:[0,0]
	v_pk_fma_f32 v[130:131], v[154:155], v[122:123], v[126:127] op_sel_hi:[0,1,1] neg_lo:[0,0,1] neg_hi:[0,0,1]
	v_pk_fma_f32 v[122:123], v[154:155], v[122:123], v[126:127] op_sel_hi:[0,1,1]
	v_mov_b32_e32 v129, v121
	v_pk_mul_f32 v[118:119], v[118:119], v[188:189] op_sel_hi:[1,0]
	v_pk_mul_f32 v[126:127], v[144:145], v[116:117] op_sel:[1,1] op_sel_hi:[1,0]
	v_mov_b32_e32 v2, v147
	v_mov_b32_e32 v131, v123
	v_pk_mul_f32 v[120:121], v[128:129], s[0:1] op_sel_hi:[1,0]
	v_pk_fma_f32 v[128:129], v[144:145], v[116:117], v[126:127] op_sel_hi:[0,1,1] neg_lo:[0,0,1] neg_hi:[0,0,1]
	v_pk_fma_f32 v[116:117], v[144:145], v[116:117], v[126:127] op_sel_hi:[0,1,1]
	v_pk_mul_f32 v[126:127], v[2:3], v[118:119] op_sel:[0,1] op_sel_hi:[0,0]
	v_pk_mul_f32 v[122:123], v[130:131], s[0:1] op_sel_hi:[1,0]
	v_pk_fma_f32 v[130:131], v[146:147], v[118:119], v[126:127] op_sel_hi:[0,1,1] neg_lo:[0,0,1] neg_hi:[0,0,1]
	v_pk_fma_f32 v[118:119], v[146:147], v[118:119], v[126:127] op_sel_hi:[0,1,1]
	v_mov_b32_e32 v131, v119
	v_mov_b32_e32 v129, v117
	v_lshlrev_b64 v[116:117], 10, v[158:159]
	v_pk_mul_f32 v[126:127], v[130:131], s[0:1] op_sel_hi:[1,0]
	v_pk_mul_f32 v[118:119], v[128:129], s[0:1] op_sel_hi:[1,0]
	v_lshl_add_u64 v[116:117], s[94:95], 0, v[116:117]
	v_lshl_add_u64 v[128:129], v[116:117], 0, v[124:125]
	v_cvt_pk_bf16_f32 v116, v120, v121
	v_cvt_pk_bf16_f32 v117, v122, v123
	v_cvt_pk_bf16_f32 v118, v118, v119
	v_cvt_pk_bf16_f32 v119, v126, v127
	v_pk_mul_f32 v[112:113], v[112:113], v[190:191] op_sel_hi:[1,0]
	global_store_dwordx4 v[128:129], v[116:119], off
	v_pk_mul_f32 v[114:115], v[114:115], v[190:191] op_sel_hi:[1,0]
	v_mov_b32_e32 v2, v139
	v_pk_mul_f32 v[116:117], v[136:137], v[112:113] op_sel:[1,1] op_sel_hi:[1,0]
	v_pk_mul_f32 v[108:109], v[108:109], v[190:191] op_sel_hi:[1,0]
	v_pk_fma_f32 v[118:119], v[136:137], v[112:113], v[116:117] op_sel_hi:[0,1,1] neg_lo:[0,0,1] neg_hi:[0,0,1]
	v_pk_fma_f32 v[112:113], v[136:137], v[112:113], v[116:117] op_sel_hi:[0,1,1]
	v_pk_mul_f32 v[116:117], v[2:3], v[114:115] op_sel:[0,1] op_sel_hi:[0,0]
	v_pk_fma_f32 v[120:121], v[138:139], v[114:115], v[116:117] op_sel_hi:[0,1,1] neg_lo:[0,0,1] neg_hi:[0,0,1]
	v_pk_fma_f32 v[114:115], v[138:139], v[114:115], v[116:117] op_sel_hi:[0,1,1]
	v_mov_b32_e32 v119, v113
	v_pk_mul_f32 v[110:111], v[110:111], v[190:191] op_sel_hi:[1,0]
	v_pk_mul_f32 v[116:117], v[132:133], v[108:109] op_sel:[1,1] op_sel_hi:[1,0]
	v_mov_b32_e32 v2, v135
	v_mov_b32_e32 v121, v115
	v_pk_mul_f32 v[112:113], v[118:119], s[0:1] op_sel_hi:[1,0]
	v_pk_fma_f32 v[118:119], v[132:133], v[108:109], v[116:117] op_sel_hi:[0,1,1] neg_lo:[0,0,1] neg_hi:[0,0,1]
	v_pk_fma_f32 v[108:109], v[132:133], v[108:109], v[116:117] op_sel_hi:[0,1,1]
	v_pk_mul_f32 v[116:117], v[2:3], v[110:111] op_sel:[0,1] op_sel_hi:[0,0]
	v_pk_mul_f32 v[114:115], v[120:121], s[0:1] op_sel_hi:[1,0]
	v_pk_fma_f32 v[120:121], v[134:135], v[110:111], v[116:117] op_sel_hi:[0,1,1] neg_lo:[0,0,1] neg_hi:[0,0,1]
	v_pk_fma_f32 v[110:111], v[134:135], v[110:111], v[116:117] op_sel_hi:[0,1,1]
	v_mov_b32_e32 v121, v111
	v_mov_b32_e32 v119, v109
	v_lshlrev_b64 v[108:109], 10, v[160:161]
	v_pk_mul_f32 v[116:117], v[120:121], s[0:1] op_sel_hi:[1,0]
	v_pk_mul_f32 v[110:111], v[118:119], s[0:1] op_sel_hi:[1,0]
	v_lshl_add_u64 v[108:109], s[94:95], 0, v[108:109]
	v_lshl_add_u64 v[118:119], v[108:109], 0, v[124:125]
	v_cvt_pk_bf16_f32 v108, v112, v113
	v_cvt_pk_bf16_f32 v109, v114, v115
	v_cvt_pk_bf16_f32 v110, v110, v111
	v_cvt_pk_bf16_f32 v111, v116, v117
	v_pk_mul_f32 v[104:105], v[104:105], v[192:193] op_sel_hi:[1,0]
	global_store_dwordx4 v[118:119], v[108:111], off
	v_pk_mul_f32 v[106:107], v[106:107], v[192:193] op_sel_hi:[1,0]
	v_mov_b32_e32 v2, v151
	v_pk_mul_f32 v[108:109], v[148:149], v[104:105] op_sel:[1,1] op_sel_hi:[1,0]
	v_pk_mul_f32 v[100:101], v[100:101], v[192:193] op_sel_hi:[1,0]
	v_pk_fma_f32 v[110:111], v[148:149], v[104:105], v[108:109] op_sel_hi:[0,1,1] neg_lo:[0,0,1] neg_hi:[0,0,1]
	v_pk_fma_f32 v[104:105], v[148:149], v[104:105], v[108:109] op_sel_hi:[0,1,1]
	v_pk_mul_f32 v[108:109], v[2:3], v[106:107] op_sel:[0,1] op_sel_hi:[0,0]
	v_pk_fma_f32 v[112:113], v[150:151], v[106:107], v[108:109] op_sel_hi:[0,1,1] neg_lo:[0,0,1] neg_hi:[0,0,1]
	v_pk_fma_f32 v[106:107], v[150:151], v[106:107], v[108:109] op_sel_hi:[0,1,1]
	v_mov_b32_e32 v111, v105
	v_pk_mul_f32 v[102:103], v[102:103], v[192:193] op_sel_hi:[1,0]
	v_pk_mul_f32 v[108:109], v[140:141], v[100:101] op_sel:[1,1] op_sel_hi:[1,0]
	v_mov_b32_e32 v2, v143
	v_mov_b32_e32 v113, v107
	v_pk_mul_f32 v[104:105], v[110:111], s[0:1] op_sel_hi:[1,0]
	v_pk_fma_f32 v[110:111], v[140:141], v[100:101], v[108:109] op_sel_hi:[0,1,1] neg_lo:[0,0,1] neg_hi:[0,0,1]
	v_pk_fma_f32 v[100:101], v[140:141], v[100:101], v[108:109] op_sel_hi:[0,1,1]
	v_pk_mul_f32 v[108:109], v[2:3], v[102:103] op_sel:[0,1] op_sel_hi:[0,0]
	v_pk_mul_f32 v[106:107], v[112:113], s[0:1] op_sel_hi:[1,0]
	v_pk_fma_f32 v[112:113], v[142:143], v[102:103], v[108:109] op_sel_hi:[0,1,1] neg_lo:[0,0,1] neg_hi:[0,0,1]
	v_pk_fma_f32 v[102:103], v[142:143], v[102:103], v[108:109] op_sel_hi:[0,1,1]
	v_mov_b32_e32 v113, v103
	v_mov_b32_e32 v111, v101
	v_lshlrev_b64 v[100:101], 10, v[162:163]
	v_pk_mul_f32 v[108:109], v[112:113], s[0:1] op_sel_hi:[1,0]
	v_pk_mul_f32 v[102:103], v[110:111], s[0:1] op_sel_hi:[1,0]
	v_lshl_add_u64 v[100:101], s[94:95], 0, v[100:101]
	v_lshl_add_u64 v[110:111], v[100:101], 0, v[124:125]
	v_cvt_pk_bf16_f32 v100, v104, v105
	v_cvt_pk_bf16_f32 v101, v106, v107
	v_cvt_pk_bf16_f32 v102, v102, v103
	v_cvt_pk_bf16_f32 v103, v108, v109
	global_store_dwordx4 v[110:111], v[100:103], off
	s_cbranch_scc1 .LBB0_166
	v_add_u32_e32 v138, 0x80, v156
	s_movk_i32 s0, 0x7cf
	v_cmp_gt_i32_e32 vcc, s20, v138
	v_and_or_b32 v2, v138, s0, 16
	v_ashrrev_i32_e32 v139, 31, v138
	v_cndmask_b32_e32 v2, v181, v2, vcc
	v_lshl_add_u64 v[112:113], v[138:139], 2, s[70:71]
	v_lshlrev_b32_e32 v2, 8, v2
	global_load_dword v148, v[112:113], off
	v_lshl_add_u64 v[100:101], v[182:183], 0, v[2:3]
	global_load_dwordx4 v[140:143], v[100:101], off offset:16
	global_load_dwordx4 v[144:147], v[100:101], off
	v_add_u32_e32 v126, 0x90, v156
	v_and_b32_e32 v2, 0x7df, v126
	v_cmp_gt_i32_e32 vcc, s20, v126
	v_add_u32_e32 v2, 16, v2
	global_load_dword v136, v[112:113], off offset:64
	v_cndmask_b32_e32 v2, v181, v2, vcc
	v_lshlrev_b32_e32 v2, 8, v2
	v_lshl_add_u64 v[100:101], v[182:183], 0, v[2:3]
	global_load_dwordx4 v[108:111], v[100:101], off offset:16
	global_load_dwordx4 v[120:123], v[100:101], off
	v_add_u32_e32 v128, 0xa0, v156
	s_movk_i32 s0, 0x7ef
	v_cmp_gt_i32_e32 vcc, s20, v128
	v_and_or_b32 v2, v128, s0, 16
	global_load_dword v132, v[112:113], off offset:128
	v_cndmask_b32_e32 v2, v181, v2, vcc
	v_lshlrev_b32_e32 v2, 8, v2
	v_lshl_add_u64 v[104:105], v[182:183], 0, v[2:3]
	global_load_dwordx4 v[100:103], v[104:105], off offset:16
	s_nop 0
	global_load_dwordx4 v[104:107], v[104:105], off
	v_add_u32_e32 v130, 0xb0, v156
	v_and_b32_e32 v2, 0x7ff, v130
	v_cmp_gt_i32_e32 vcc, s20, v130
	v_add_u32_e32 v2, 16, v2
	global_load_dword v134, v[112:113], off offset:192
	v_cndmask_b32_e32 v2, v181, v2, vcc
	v_lshlrev_b32_e32 v2, 8, v2
	v_lshl_add_u64 v[116:117], v[182:183], 0, v[2:3]
	global_load_dwordx4 v[112:115], v[116:117], off offset:16
	s_nop 0
	global_load_dwordx4 v[116:119], v[116:117], off
	s_mov_b32 s0, 0x3e000000
	v_ashrrev_i32_e32 v127, 31, v126
	v_ashrrev_i32_e32 v129, 31, v128
	v_ashrrev_i32_e32 v131, 31, v130
	s_waitcnt vmcnt(0)
	v_pk_mul_f32 v[96:97], v[96:97], v[148:149] op_sel_hi:[1,0]
	v_pk_mul_f32 v[98:99], v[98:99], v[148:149] op_sel_hi:[1,0]
	v_pk_mul_f32 v[150:151], v[144:145], v[96:97] op_sel:[1,1] op_sel_hi:[1,0]
	v_mov_b32_e32 v2, v147
	v_pk_fma_f32 v[152:153], v[144:145], v[96:97], v[150:151] op_sel_hi:[0,1,1] neg_lo:[0,0,1] neg_hi:[0,0,1]
	v_pk_fma_f32 v[96:97], v[144:145], v[96:97], v[150:151] op_sel_hi:[0,1,1]
	v_pk_mul_f32 v[144:145], v[2:3], v[98:99] op_sel:[0,1] op_sel_hi:[0,0]
	v_pk_mul_f32 v[92:93], v[92:93], v[148:149] op_sel_hi:[1,0]
	v_pk_fma_f32 v[150:151], v[146:147], v[98:99], v[144:145] op_sel_hi:[0,1,1] neg_lo:[0,0,1] neg_hi:[0,0,1]
	v_pk_fma_f32 v[98:99], v[146:147], v[98:99], v[144:145] op_sel_hi:[0,1,1]
	v_pk_mul_f32 v[94:95], v[94:95], v[148:149] op_sel_hi:[1,0]
	v_pk_mul_f32 v[144:145], v[140:141], v[92:93] op_sel:[1,1] op_sel_hi:[1,0]
	v_mov_b32_e32 v2, v143
	v_pk_fma_f32 v[146:147], v[140:141], v[92:93], v[144:145] op_sel_hi:[0,1,1] neg_lo:[0,0,1] neg_hi:[0,0,1]
	v_pk_fma_f32 v[92:93], v[140:141], v[92:93], v[144:145] op_sel_hi:[0,1,1]
	v_pk_mul_f32 v[140:141], v[2:3], v[94:95] op_sel:[0,1] op_sel_hi:[0,0]
	v_pk_fma_f32 v[144:145], v[142:143], v[94:95], v[140:141] op_sel_hi:[0,1,1] neg_lo:[0,0,1] neg_hi:[0,0,1]
	v_pk_fma_f32 v[94:95], v[142:143], v[94:95], v[140:141] op_sel_hi:[0,1,1]
	v_mov_b32_e32 v151, v99
	v_mov_b32_e32 v153, v97
	v_mov_b32_e32 v145, v95
	v_mov_b32_e32 v147, v93
	v_lshlrev_b64 v[92:93], 10, v[138:139]
	v_pk_mul_f32 v[98:99], v[150:151], s[0:1] op_sel_hi:[1,0]
	v_pk_mul_f32 v[96:97], v[152:153], s[0:1] op_sel_hi:[1,0]
	v_pk_mul_f32 v[140:141], v[144:145], s[0:1] op_sel_hi:[1,0]
	v_pk_mul_f32 v[94:95], v[146:147], s[0:1] op_sel_hi:[1,0]
	v_lshl_add_u64 v[92:93], s[94:95], 0, v[92:93]
	v_lshl_add_u64 v[138:139], v[92:93], 0, v[124:125]
	v_cvt_pk_bf16_f32 v92, v96, v97
	v_cvt_pk_bf16_f32 v93, v98, v99
	v_cvt_pk_bf16_f32 v94, v94, v95
	v_cvt_pk_bf16_f32 v95, v140, v141
	v_pk_mul_f32 v[88:89], v[88:89], v[136:137] op_sel_hi:[1,0]
	global_store_dwordx4 v[138:139], v[92:95], off
	v_pk_mul_f32 v[90:91], v[90:91], v[136:137] op_sel_hi:[1,0]
	v_mov_b32_e32 v2, v123
	v_pk_mul_f32 v[92:93], v[120:121], v[88:89] op_sel:[1,1] op_sel_hi:[1,0]
	v_pk_mul_f32 v[84:85], v[84:85], v[136:137] op_sel_hi:[1,0]
	v_pk_fma_f32 v[94:95], v[120:121], v[88:89], v[92:93] op_sel_hi:[0,1,1] neg_lo:[0,0,1] neg_hi:[0,0,1]
	v_pk_fma_f32 v[88:89], v[120:121], v[88:89], v[92:93] op_sel_hi:[0,1,1]
	v_pk_mul_f32 v[92:93], v[2:3], v[90:91] op_sel:[0,1] op_sel_hi:[0,0]
	v_pk_fma_f32 v[96:97], v[122:123], v[90:91], v[92:93] op_sel_hi:[0,1,1] neg_lo:[0,0,1] neg_hi:[0,0,1]
	v_pk_fma_f32 v[90:91], v[122:123], v[90:91], v[92:93] op_sel_hi:[0,1,1]
	v_mov_b32_e32 v95, v89
	v_pk_mul_f32 v[86:87], v[86:87], v[136:137] op_sel_hi:[1,0]
	v_pk_mul_f32 v[92:93], v[108:109], v[84:85] op_sel:[1,1] op_sel_hi:[1,0]
	v_mov_b32_e32 v2, v111
	v_mov_b32_e32 v97, v91
	v_pk_mul_f32 v[88:89], v[94:95], s[0:1] op_sel_hi:[1,0]
	v_pk_fma_f32 v[94:95], v[108:109], v[84:85], v[92:93] op_sel_hi:[0,1,1] neg_lo:[0,0,1] neg_hi:[0,0,1]
	v_pk_fma_f32 v[84:85], v[108:109], v[84:85], v[92:93] op_sel_hi:[0,1,1]
	v_pk_mul_f32 v[92:93], v[2:3], v[86:87] op_sel:[0,1] op_sel_hi:[0,0]
	v_pk_mul_f32 v[90:91], v[96:97], s[0:1] op_sel_hi:[1,0]
	v_pk_fma_f32 v[96:97], v[110:111], v[86:87], v[92:93] op_sel_hi:[0,1,1] neg_lo:[0,0,1] neg_hi:[0,0,1]
	v_pk_fma_f32 v[86:87], v[110:111], v[86:87], v[92:93] op_sel_hi:[0,1,1]
	v_mov_b32_e32 v97, v87
	v_mov_b32_e32 v95, v85
	v_lshlrev_b64 v[84:85], 10, v[126:127]
	v_pk_mul_f32 v[92:93], v[96:97], s[0:1] op_sel_hi:[1,0]
	v_pk_mul_f32 v[86:87], v[94:95], s[0:1] op_sel_hi:[1,0]
	v_lshl_add_u64 v[84:85], s[94:95], 0, v[84:85]
	v_lshl_add_u64 v[94:95], v[84:85], 0, v[124:125]
	v_cvt_pk_bf16_f32 v84, v88, v89
	v_cvt_pk_bf16_f32 v85, v90, v91
	v_cvt_pk_bf16_f32 v86, v86, v87
	v_cvt_pk_bf16_f32 v87, v92, v93
	v_pk_mul_f32 v[80:81], v[80:81], v[132:133] op_sel_hi:[1,0]
	global_store_dwordx4 v[94:95], v[84:87], off
	v_pk_mul_f32 v[82:83], v[82:83], v[132:133] op_sel_hi:[1,0]
	v_mov_b32_e32 v2, v107
	v_pk_mul_f32 v[84:85], v[104:105], v[80:81] op_sel:[1,1] op_sel_hi:[1,0]
	v_pk_mul_f32 v[76:77], v[76:77], v[132:133] op_sel_hi:[1,0]
	v_pk_fma_f32 v[86:87], v[104:105], v[80:81], v[84:85] op_sel_hi:[0,1,1] neg_lo:[0,0,1] neg_hi:[0,0,1]
	v_pk_fma_f32 v[80:81], v[104:105], v[80:81], v[84:85] op_sel_hi:[0,1,1]
	v_pk_mul_f32 v[84:85], v[2:3], v[82:83] op_sel:[0,1] op_sel_hi:[0,0]
	v_pk_fma_f32 v[88:89], v[106:107], v[82:83], v[84:85] op_sel_hi:[0,1,1] neg_lo:[0,0,1] neg_hi:[0,0,1]
	v_pk_fma_f32 v[82:83], v[106:107], v[82:83], v[84:85] op_sel_hi:[0,1,1]
	v_mov_b32_e32 v87, v81
	v_pk_mul_f32 v[78:79], v[78:79], v[132:133] op_sel_hi:[1,0]
	v_pk_mul_f32 v[84:85], v[100:101], v[76:77] op_sel:[1,1] op_sel_hi:[1,0]
	v_mov_b32_e32 v2, v103
	v_mov_b32_e32 v89, v83
	v_pk_mul_f32 v[80:81], v[86:87], s[0:1] op_sel_hi:[1,0]
	v_pk_fma_f32 v[86:87], v[100:101], v[76:77], v[84:85] op_sel_hi:[0,1,1] neg_lo:[0,0,1] neg_hi:[0,0,1]
	v_pk_fma_f32 v[76:77], v[100:101], v[76:77], v[84:85] op_sel_hi:[0,1,1]
	v_pk_mul_f32 v[84:85], v[2:3], v[78:79] op_sel:[0,1] op_sel_hi:[0,0]
	v_pk_mul_f32 v[82:83], v[88:89], s[0:1] op_sel_hi:[1,0]
	v_pk_fma_f32 v[88:89], v[102:103], v[78:79], v[84:85] op_sel_hi:[0,1,1] neg_lo:[0,0,1] neg_hi:[0,0,1]
	v_pk_fma_f32 v[78:79], v[102:103], v[78:79], v[84:85] op_sel_hi:[0,1,1]
	v_mov_b32_e32 v89, v79
	v_mov_b32_e32 v87, v77
	v_lshlrev_b64 v[76:77], 10, v[128:129]
	v_pk_mul_f32 v[84:85], v[88:89], s[0:1] op_sel_hi:[1,0]
	v_pk_mul_f32 v[78:79], v[86:87], s[0:1] op_sel_hi:[1,0]
	v_lshl_add_u64 v[76:77], s[94:95], 0, v[76:77]
	v_lshl_add_u64 v[86:87], v[76:77], 0, v[124:125]
	v_cvt_pk_bf16_f32 v76, v80, v81
	v_cvt_pk_bf16_f32 v77, v82, v83
	v_cvt_pk_bf16_f32 v78, v78, v79
	v_cvt_pk_bf16_f32 v79, v84, v85
	v_pk_mul_f32 v[72:73], v[72:73], v[134:135] op_sel_hi:[1,0]
	global_store_dwordx4 v[86:87], v[76:79], off
	v_pk_mul_f32 v[74:75], v[74:75], v[134:135] op_sel_hi:[1,0]
	v_mov_b32_e32 v2, v119
	v_pk_mul_f32 v[76:77], v[116:117], v[72:73] op_sel:[1,1] op_sel_hi:[1,0]
	v_pk_mul_f32 v[68:69], v[68:69], v[134:135] op_sel_hi:[1,0]
	v_pk_fma_f32 v[78:79], v[116:117], v[72:73], v[76:77] op_sel_hi:[0,1,1] neg_lo:[0,0,1] neg_hi:[0,0,1]
	v_pk_fma_f32 v[72:73], v[116:117], v[72:73], v[76:77] op_sel_hi:[0,1,1]
	v_pk_mul_f32 v[76:77], v[2:3], v[74:75] op_sel:[0,1] op_sel_hi:[0,0]
	v_pk_fma_f32 v[80:81], v[118:119], v[74:75], v[76:77] op_sel_hi:[0,1,1] neg_lo:[0,0,1] neg_hi:[0,0,1]
	v_pk_fma_f32 v[74:75], v[118:119], v[74:75], v[76:77] op_sel_hi:[0,1,1]
	v_mov_b32_e32 v79, v73
	v_pk_mul_f32 v[70:71], v[70:71], v[134:135] op_sel_hi:[1,0]
	v_pk_mul_f32 v[76:77], v[112:113], v[68:69] op_sel:[1,1] op_sel_hi:[1,0]
	v_mov_b32_e32 v2, v115
	v_mov_b32_e32 v81, v75
	v_pk_mul_f32 v[72:73], v[78:79], s[0:1] op_sel_hi:[1,0]
	v_pk_fma_f32 v[78:79], v[112:113], v[68:69], v[76:77] op_sel_hi:[0,1,1] neg_lo:[0,0,1] neg_hi:[0,0,1]
	v_pk_fma_f32 v[68:69], v[112:113], v[68:69], v[76:77] op_sel_hi:[0,1,1]
	v_pk_mul_f32 v[76:77], v[2:3], v[70:71] op_sel:[0,1] op_sel_hi:[0,0]
	v_pk_mul_f32 v[74:75], v[80:81], s[0:1] op_sel_hi:[1,0]
	v_pk_fma_f32 v[80:81], v[114:115], v[70:71], v[76:77] op_sel_hi:[0,1,1] neg_lo:[0,0,1] neg_hi:[0,0,1]
	v_pk_fma_f32 v[70:71], v[114:115], v[70:71], v[76:77] op_sel_hi:[0,1,1]
	v_mov_b32_e32 v81, v71
	v_mov_b32_e32 v79, v69
	v_lshlrev_b64 v[68:69], 10, v[130:131]
	v_pk_mul_f32 v[76:77], v[80:81], s[0:1] op_sel_hi:[1,0]
	v_pk_mul_f32 v[70:71], v[78:79], s[0:1] op_sel_hi:[1,0]
	v_lshl_add_u64 v[68:69], s[94:95], 0, v[68:69]
	v_lshl_add_u64 v[78:79], v[68:69], 0, v[124:125]
	v_cvt_pk_bf16_f32 v68, v72, v73
	v_cvt_pk_bf16_f32 v69, v74, v75
	v_cvt_pk_bf16_f32 v70, v70, v71
	v_cvt_pk_bf16_f32 v71, v76, v77
	global_store_dwordx4 v[78:79], v[68:71], off

.LBB0_235:
	s_andn2_b64 vcc, exec, s[0:1]
	s_cbranch_vccnz .LBB0_238
	s_lshl_b32 s1, s48, 8
	s_add_i32 s1, s1, s31
	v_add_u32_e32 v91, s1, v181
	v_lshlrev_b32_e32 v91, 2, v91
	global_load_dword v68, v91, s[70:71]
	global_load_dword v69, v91, s[70:71] offset:64
	global_load_dword v70, v91, s[70:71] offset:128
	global_load_dword v71, v91, s[70:71] offset:192
	global_load_dword v72, v91, s[70:71] offset:512
	global_load_dword v73, v91, s[70:71] offset:576
	global_load_dword v74, v91, s[70:71] offset:640
	global_load_dword v75, v91, s[70:71] offset:704
	s_add_i32 s3, s74, s49
	s_addk_i32 s3, 0x80
	s_bfe_u32 s2, s3, 0x30006
	s_lshl_b32 s0, s2, 2
	v_mov_b32_e32 v116, s0
	global_load_dword v108, v116, s[80:81]
	global_load_dword v109, v116, s[80:81] offset:32
	s_and_b32 s42, s3, 63
	s_lshl_b32 s0, s31, 7
	s_lshl_b32 s44, s49, 6
	s_add_i32 s0, s0, s44
	s_add_i32 s0, s0, 0x20d40
	v_bfe_u32 v91, v213, 4, 2
	v_lshlrev_b32_e32 v116, 4, v91
	v_and_b32_e32 v110, 8, v181
	v_lshlrev_b32_e32 v110, 2, v110
	v_xor_b32_e32 v116, v116, v110
	v_lshl_add_u32 v84, v181, 6, v116
	v_add_u32_e32 v84, s0, v84
	v_bfe_u32 v116, v213, 2, 2
	v_lshl_add_u32 v116, v91, 3, v116
	v_lshlrev_b32_e32 v116, 6, v116
	v_and_b32_e32 v110, 1, v91
	v_lshl_add_u32 v116, v110, 5, v116
	v_and_b32_e32 v110, 3, v213
	v_lshl_add_u32 v116, v110, 3, v116
	v_add_u32_e32 v85, s0, v116
	v_xor_b32_e32 v116, 32, v116
	v_add_u32_e32 v86, s0, v116
	v_lshlrev_b32_e32 v89, 10, v181
	v_lshl_add_u32 v89, v91, 4, v89
	s_lshl_b32 s44, s42, 2
	v_lshl_add_u32 v90, v91, 5, s44
	v_lshl_add_u32 v90, v181, 8, v90
	v_add_u32_e32 v116, s42, v181
	v_mul_u32_u24_e32 v116, 0x1100, v116
	v_readlane_b32 s4, v251, 9
	v_readlane_b32 s5, v251, 10
	v_readlane_b32 s36, v251, 7
	v_readlane_b32 s37, v251, 8
	v_readlane_b32 s40, v251, 5
	v_readlane_b32 s41, v251, 6
	s_lshl_b32 s44, s3, 1
	s_add_u32 s16, s94, s44
	s_addc_u32 s17, s95, 0
	s_add_u32 s16, s16, 0x101fc00
	s_addc_u32 s17, s17, 0
	s_lshl_b32 s44, s1, 10
	s_add_u32 s16, s16, s44
	s_addc_u32 s17, s17, 0
	s_cmp_eq_u32 s48, 64
	s_cbranch_scc1 .Lsec1_b_meta
	v_lshl_add_u32 v87, v91, 4, v116
	v_add_u32_e32 v110, s31, v181
	s_lshr_b32 s44, s48, 3
	s_lshl_b32 s44, s44, 3
	s_add_i32 s44, s44, s2
	s_mul_i32 s44, s44, 0x44000
	s_and_b32 s45, s48, 7
	s_lshl_b32 s45, s45, 8
	s_add_i32 s45, s45, s31
	s_lshl_b32 s47, s45, 1
	s_add_i32 s44, s44, s47
	s_addk_i32 s44, 0x100
	s_add_i32 s45, s45, 16
	s_lshl_b32 s45, s45, 8
	s_movk_i32 s21, 0x1000
	s_mov_b32 s43, 64
	s_mov_b32 s3, 16
	s_branch .Lsec1_b_go
.Lsec1_b_meta:
	v_lshrrev_b32_e32 v110, 1, v91
	v_mul_u32_u24_e32 v110, 0x220000, v110
	v_and_b32_e32 v87, 1, v91
	v_lshl_add_u32 v87, v87, 4, v116
	v_add_u32_e32 v87, v87, v110
	v_add_u32_e32 v110, 0x70, v181
	s_mul_i32 s44, s2, 0x44000
	s_lshr_b32 s45, s31, 6
	s_mul_i32 s45, s45, 0x880000
	s_add_i32 s44, s44, s45
	s_addk_i32 s44, 0xe0
	s_mov_b32 s45, 0
	s_mov_b32 s21, 0
	s_mov_b32 s43, 0x440000
	s_mov_b32 s3, 0
.Lsec1_b_go:
	s_nop 3
	s_add_u32 s36, s36, s44
	s_addc_u32 s37, s37, 0
	s_add_u32 s40, s40, s44
	s_addc_u32 s41, s41, 0
	s_add_u32 s4, s4, s45
	s_addc_u32 s5, s5, 0
	v_add_u32_e32 v88, 0x11000, v87
	global_load_dwordx4 v[92:95], v90, s[4:5]
	global_load_dwordx4 v[96:99], v90, s[4:5] offset:16
	s_waitcnt vmcnt(2)
	v_mul_f32_e32 v108, 0x3fb8aa3b, v108
	v_exp_f32_e32 v108, v108
	v_mul_f32_e32 v109, 0x3fb8aa3b, v109
	v_exp_f32_e32 v109, v109
	v_sub_u32_e32 v76, 0x7f, v110
	v_cvt_f32_u32_e32 v76, v76
	v_mul_f32_e64 v76, v76, -v108
	v_mul_f32_e32 v76, 0x3fb8aa3b, v76
	v_exp_f32_e32 v76, v76
	v_cvt_f32_u32_e32 v80, v110
	v_mul_f32_e64 v80, v80, -v109
	v_mul_f32_e32 v80, 0x3fb8aa3b, v80
	v_exp_f32_e32 v80, v80
	v_add_u32_e32 v110, s3, v110
	v_sub_u32_e32 v77, 0x7f, v110
	v_cvt_f32_u32_e32 v77, v77
	v_mul_f32_e64 v77, v77, -v108
	v_mul_f32_e32 v77, 0x3fb8aa3b, v77
	v_exp_f32_e32 v77, v77
	v_cvt_f32_u32_e32 v81, v110
	v_mul_f32_e64 v81, v81, -v109
	v_mul_f32_e32 v81, 0x3fb8aa3b, v81
	v_exp_f32_e32 v81, v81
	v_add_u32_e32 v110, s3, v110
	v_sub_u32_e32 v78, 0x7f, v110
	v_cvt_f32_u32_e32 v78, v78
	v_mul_f32_e64 v78, v78, -v108
	v_mul_f32_e32 v78, 0x3fb8aa3b, v78
	v_exp_f32_e32 v78, v78
	v_cvt_f32_u32_e32 v82, v110
	v_mul_f32_e64 v82, v82, -v109
	v_mul_f32_e32 v82, 0x3fb8aa3b, v82
	v_exp_f32_e32 v82, v82
	v_add_u32_e32 v110, s3, v110
	v_sub_u32_e32 v79, 0x7f, v110
	v_cvt_f32_u32_e32 v79, v79
	v_mul_f32_e64 v79, v79, -v108
	v_mul_f32_e32 v79, 0x3fb8aa3b, v79
	v_exp_f32_e32 v79, v79
	v_cvt_f32_u32_e32 v83, v110
	v_mul_f32_e64 v83, v83, -v109
	v_mul_f32_e32 v83, 0x3fb8aa3b, v83
	v_exp_f32_e32 v83, v83
	s_add_u32 s4, s4, s21
	s_addc_u32 s5, s5, 0
	global_load_dwordx4 v[100:103], v90, s[4:5]
	global_load_dwordx4 v[104:107], v90, s[4:5] offset:16
	s_waitcnt vmcnt(2)
	v_mul_f32_e32 v108, v68, v64
	v_mul_f32_e32 v109, v68, v65
	v_mul_f32_e32 v110, v68, v66
	v_mul_f32_e32 v111, v68, v67
	v_mul_f32_e32 v112, v68, v60
	v_mul_f32_e32 v113, v68, v61
	v_mul_f32_e32 v114, v68, v62
	v_mul_f32_e32 v115, v68, v63
	v_mul_f32_e32 v91, v93, v109
	v_mul_f32_e32 v116, v93, v108
	v_fma_f32 v108, v92, v108, -v91
	v_fma_f32 v109, v92, v109, v116
	v_mul_f32_e32 v91, v95, v111
	v_mul_f32_e32 v116, v95, v110
	v_fma_f32 v110, v94, v110, -v91
	v_fma_f32 v111, v94, v111, v116
	v_mul_f32_e32 v91, v97, v113
	v_mul_f32_e32 v116, v97, v112
	v_fma_f32 v112, v96, v112, -v91
	v_fma_f32 v113, v96, v113, v116
	v_mul_f32_e32 v91, v99, v115
	v_mul_f32_e32 v116, v99, v114
	v_fma_f32 v114, v98, v114, -v91
	v_fma_f32 v115, v98, v115, v116
	v_cvt_pk_bf16_f32 v120, v108, v109
	v_cvt_pk_bf16_f32 v121, v110, v111
	v_cvt_pk_bf16_f32 v122, v112, v113
	v_cvt_pk_bf16_f32 v123, v114, v115
	global_store_dwordx4 v89, v[120:123], s[16:17]
	s_add_u32 s16, s16, 0x4000
	s_addc_u32 s17, s17, 0
	v_mul_f32_e32 v91, v76, v108
	v_mul_f32_e32 v116, v76, v109
	v_cvt_pk_bf16_f32 v124, v91, v116
	v_mul_f32_e32 v91, v76, v110
	v_mul_f32_e32 v116, v76, v111
	v_cvt_pk_bf16_f32 v125, v91, v116
	v_mul_f32_e32 v91, v76, v112
	v_mul_f32_e32 v116, v76, v113
	v_cvt_pk_bf16_f32 v126, v91, v116
	v_mul_f32_e32 v91, v76, v114
	v_mul_f32_e32 v116, v76, v115
	v_cvt_pk_bf16_f32 v127, v91, v116
	ds_write_b128 v84, v[124:127]
	v_mul_f32_e32 v91, v80, v108
	v_mul_f32_e32 v116, v80, v109
	v_cvt_pk_bf16_f32 v128, v91, v116
	v_mul_f32_e32 v91, v80, v110
	v_mul_f32_e32 v116, v80, v111
	v_cvt_pk_bf16_f32 v129, v91, v116
	v_mul_f32_e32 v91, v80, v112
	v_mul_f32_e32 v116, v80, v113
	v_cvt_pk_bf16_f32 v130, v91, v116
	v_mul_f32_e32 v91, v80, v114
	v_mul_f32_e32 v116, v80, v115
	v_cvt_pk_bf16_f32 v131, v91, v116
	s_add_u32 s4, s4, s21
	s_addc_u32 s5, s5, 0
	global_load_dwordx4 v[92:95], v90, s[4:5]
	global_load_dwordx4 v[96:99], v90, s[4:5] offset:16
	s_waitcnt vmcnt(2)
	v_mul_f32_e32 v108, v69, v56
	v_mul_f32_e32 v109, v69, v57
	v_mul_f32_e32 v110, v69, v58
	v_mul_f32_e32 v111, v69, v59
	v_mul_f32_e32 v112, v69, v52
	v_mul_f32_e32 v113, v69, v53
	v_mul_f32_e32 v114, v69, v54
	v_mul_f32_e32 v115, v69, v55
	v_mul_f32_e32 v91, v101, v109
	v_mul_f32_e32 v116, v101, v108
	v_fma_f32 v108, v100, v108, -v91
	v_fma_f32 v109, v100, v109, v116
	v_mul_f32_e32 v91, v103, v111
	v_mul_f32_e32 v116, v103, v110
	v_fma_f32 v110, v102, v110, -v91
	v_fma_f32 v111, v102, v111, v116
	v_mul_f32_e32 v91, v105, v113
	v_mul_f32_e32 v116, v105, v112
	v_fma_f32 v112, v104, v112, -v91
	v_fma_f32 v113, v104, v113, v116
	v_mul_f32_e32 v91, v107, v115
	v_mul_f32_e32 v116, v107, v114
	v_fma_f32 v114, v106, v114, -v91
	v_fma_f32 v115, v106, v115, v116
	v_cvt_pk_bf16_f32 v120, v108, v109
	v_cvt_pk_bf16_f32 v121, v110, v111
	v_cvt_pk_bf16_f32 v122, v112, v113
	v_cvt_pk_bf16_f32 v123, v114, v115
	global_store_dwordx4 v89, v[120:123], s[16:17]
	s_add_u32 s16, s16, 0x4000
	s_addc_u32 s17, s17, 0
	v_mul_f32_e32 v91, v77, v108
	v_mul_f32_e32 v116, v77, v109
	v_cvt_pk_bf16_f32 v124, v91, v116
	v_mul_f32_e32 v91, v77, v110
	v_mul_f32_e32 v116, v77, v111
	v_cvt_pk_bf16_f32 v125, v91, v116
	v_mul_f32_e32 v91, v77, v112
	v_mul_f32_e32 v116, v77, v113
	v_cvt_pk_bf16_f32 v126, v91, v116
	v_mul_f32_e32 v91, v77, v114
	v_mul_f32_e32 v116, v77, v115
	v_cvt_pk_bf16_f32 v127, v91, v116
	ds_write_b128 v84, v[124:127] offset:1024
	v_mul_f32_e32 v91, v81, v108
	v_mul_f32_e32 v116, v81, v109
	v_cvt_pk_bf16_f32 v132, v91, v116
	v_mul_f32_e32 v91, v81, v110
	v_mul_f32_e32 v116, v81, v111
	v_cvt_pk_bf16_f32 v133, v91, v116
	v_mul_f32_e32 v91, v81, v112
	v_mul_f32_e32 v116, v81, v113
	v_cvt_pk_bf16_f32 v134, v91, v116
	v_mul_f32_e32 v91, v81, v114
	v_mul_f32_e32 v116, v81, v115
	v_cvt_pk_bf16_f32 v135, v91, v116
	ds_read_b64_tr_b16 v[120:121], v85
	ds_read_b64_tr_b16 v[122:123], v85 offset:256
	ds_read_b64_tr_b16 v[124:125], v86
	ds_read_b64_tr_b16 v[126:127], v86 offset:256
	s_waitcnt lgkmcnt(0)
	global_store_dwordx4 v87, v[120:123], s[36:37]
	global_store_dwordx4 v88, v[124:127], s[36:37]
	ds_write_b128 v84, v[128:131]
	ds_write_b128 v84, v[132:135] offset:1024
	s_nop 1
	ds_read_b64_tr_b16 v[120:121], v85
	ds_read_b64_tr_b16 v[122:123], v85 offset:256
	ds_read_b64_tr_b16 v[124:125], v86
	ds_read_b64_tr_b16 v[126:127], v86 offset:256
	s_waitcnt lgkmcnt(0)
	global_store_dwordx4 v87, v[120:123], s[40:41]
	global_store_dwordx4 v88, v[124:127], s[40:41]
	s_add_u32 s36, s36, s43
	s_addc_u32 s37, s37, 0
	s_add_u32 s40, s40, s43
	s_addc_u32 s41, s41, 0
	s_add_u32 s4, s4, s21
	s_addc_u32 s5, s5, 0
	global_load_dwordx4 v[100:103], v90, s[4:5]
	global_load_dwordx4 v[104:107], v90, s[4:5] offset:16
	s_waitcnt vmcnt(2)
	v_mul_f32_e32 v108, v70, v48
	v_mul_f32_e32 v109, v70, v49
	v_mul_f32_e32 v110, v70, v50
	v_mul_f32_e32 v111, v70, v51
	v_mul_f32_e32 v112, v70, v44
	v_mul_f32_e32 v113, v70, v45
	v_mul_f32_e32 v114, v70, v46
	v_mul_f32_e32 v115, v70, v47
	v_mul_f32_e32 v91, v93, v109
	v_mul_f32_e32 v116, v93, v108
	v_fma_f32 v108, v92, v108, -v91
	v_fma_f32 v109, v92, v109, v116
	v_mul_f32_e32 v91, v95, v111
	v_mul_f32_e32 v116, v95, v110
	v_fma_f32 v110, v94, v110, -v91
	v_fma_f32 v111, v94, v111, v116
	v_mul_f32_e32 v91, v97, v113
	v_mul_f32_e32 v116, v97, v112
	v_fma_f32 v112, v96, v112, -v91
	v_fma_f32 v113, v96, v113, v116
	v_mul_f32_e32 v91, v99, v115
	v_mul_f32_e32 v116, v99, v114
	v_fma_f32 v114, v98, v114, -v91
	v_fma_f32 v115, v98, v115, v116
	v_cvt_pk_bf16_f32 v120, v108, v109
	v_cvt_pk_bf16_f32 v121, v110, v111
	v_cvt_pk_bf16_f32 v122, v112, v113
	v_cvt_pk_bf16_f32 v123, v114, v115
	global_store_dwordx4 v89, v[120:123], s[16:17]
	s_add_u32 s16, s16, 0x4000
	s_addc_u32 s17, s17, 0
	v_mul_f32_e32 v91, v78, v108
	v_mul_f32_e32 v116, v78, v109
	v_cvt_pk_bf16_f32 v124, v91, v116
	v_mul_f32_e32 v91, v78, v110
	v_mul_f32_e32 v116, v78, v111
	v_cvt_pk_bf16_f32 v125, v91, v116
	v_mul_f32_e32 v91, v78, v112
	v_mul_f32_e32 v116, v78, v113
	v_cvt_pk_bf16_f32 v126, v91, v116
	v_mul_f32_e32 v91, v78, v114
	v_mul_f32_e32 v116, v78, v115
	v_cvt_pk_bf16_f32 v127, v91, v116
	ds_write_b128 v84, v[124:127]
	v_mul_f32_e32 v91, v82, v108
	v_mul_f32_e32 v116, v82, v109
	v_cvt_pk_bf16_f32 v128, v91, v116
	v_mul_f32_e32 v91, v82, v110
	v_mul_f32_e32 v116, v82, v111
	v_cvt_pk_bf16_f32 v129, v91, v116
	v_mul_f32_e32 v91, v82, v112
	v_mul_f32_e32 v116, v82, v113
	v_cvt_pk_bf16_f32 v130, v91, v116
	v_mul_f32_e32 v91, v82, v114
	v_mul_f32_e32 v116, v82, v115
	v_cvt_pk_bf16_f32 v131, v91, v116
	s_add_u32 s4, s4, 0x5000
	s_addc_u32 s5, s5, 0
	global_load_dwordx4 v[92:95], v90, s[4:5]
	global_load_dwordx4 v[96:99], v90, s[4:5] offset:16
	s_waitcnt vmcnt(2)
	v_mul_f32_e32 v108, v71, v40
	v_mul_f32_e32 v109, v71, v41
	v_mul_f32_e32 v110, v71, v42
	v_mul_f32_e32 v111, v71, v43
	v_mul_f32_e32 v112, v71, v36
	v_mul_f32_e32 v113, v71, v37
	v_mul_f32_e32 v114, v71, v38
	v_mul_f32_e32 v115, v71, v39
	v_mul_f32_e32 v91, v101, v109
	v_mul_f32_e32 v116, v101, v108
	v_fma_f32 v108, v100, v108, -v91
	v_fma_f32 v109, v100, v109, v116
	v_mul_f32_e32 v91, v103, v111
	v_mul_f32_e32 v116, v103, v110
	v_fma_f32 v110, v102, v110, -v91
	v_fma_f32 v111, v102, v111, v116
	v_mul_f32_e32 v91, v105, v113
	v_mul_f32_e32 v116, v105, v112
	v_fma_f32 v112, v104, v112, -v91
	v_fma_f32 v113, v104, v113, v116
	v_mul_f32_e32 v91, v107, v115
	v_mul_f32_e32 v116, v107, v114
	v_fma_f32 v114, v106, v114, -v91
	v_fma_f32 v115, v106, v115, v116
	v_cvt_pk_bf16_f32 v120, v108, v109
	v_cvt_pk_bf16_f32 v121, v110, v111
	v_cvt_pk_bf16_f32 v122, v112, v113
	v_cvt_pk_bf16_f32 v123, v114, v115
	global_store_dwordx4 v89, v[120:123], s[16:17]
	s_add_u32 s16, s16, 0x14000
	s_addc_u32 s17, s17, 0
	v_mul_f32_e32 v91, v79, v108
	v_mul_f32_e32 v116, v79, v109
	v_cvt_pk_bf16_f32 v124, v91, v116
	v_mul_f32_e32 v91, v79, v110
	v_mul_f32_e32 v116, v79, v111
	v_cvt_pk_bf16_f32 v125, v91, v116
	v_mul_f32_e32 v91, v79, v112
	v_mul_f32_e32 v116, v79, v113
	v_cvt_pk_bf16_f32 v126, v91, v116
	v_mul_f32_e32 v91, v79, v114
	v_mul_f32_e32 v116, v79, v115
	v_cvt_pk_bf16_f32 v127, v91, v116
	ds_write_b128 v84, v[124:127] offset:1024
	v_mul_f32_e32 v91, v83, v108
	v_mul_f32_e32 v116, v83, v109
	v_cvt_pk_bf16_f32 v132, v91, v116
	v_mul_f32_e32 v91, v83, v110
	v_mul_f32_e32 v116, v83, v111
	v_cvt_pk_bf16_f32 v133, v91, v116
	v_mul_f32_e32 v91, v83, v112
	v_mul_f32_e32 v116, v83, v113
	v_cvt_pk_bf16_f32 v134, v91, v116
	v_mul_f32_e32 v91, v83, v114
	v_mul_f32_e32 v116, v83, v115
	v_cvt_pk_bf16_f32 v135, v91, v116
	ds_read_b64_tr_b16 v[120:121], v85
	ds_read_b64_tr_b16 v[122:123], v85 offset:256
	ds_read_b64_tr_b16 v[124:125], v86
	ds_read_b64_tr_b16 v[126:127], v86 offset:256
	s_waitcnt lgkmcnt(0)
	global_store_dwordx4 v87, v[120:123], s[36:37]
	global_store_dwordx4 v88, v[124:127], s[36:37]
	ds_write_b128 v84, v[128:131]
	ds_write_b128 v84, v[132:135] offset:1024
	s_nop 1
	ds_read_b64_tr_b16 v[120:121], v85
	ds_read_b64_tr_b16 v[122:123], v85 offset:256
	ds_read_b64_tr_b16 v[124:125], v86
	ds_read_b64_tr_b16 v[126:127], v86 offset:256
	s_waitcnt lgkmcnt(0)
	global_store_dwordx4 v87, v[120:123], s[40:41]
	global_store_dwordx4 v88, v[124:127], s[40:41]
	s_add_u32 s36, s36, 0xc0
	s_addc_u32 s37, s37, 0
	s_add_u32 s40, s40, 0xc0
	s_addc_u32 s41, s41, 0
	s_cmp_eq_u32 s48, 64
	s_cbranch_scc1 .Lsec1_b_done
	s_add_u32 s4, s4, s21
	s_addc_u32 s5, s5, 0
	global_load_dwordx4 v[100:103], v90, s[4:5]
	global_load_dwordx4 v[104:107], v90, s[4:5] offset:16
	s_waitcnt vmcnt(2)
	v_mul_f32_e32 v108, v72, v32
	v_mul_f32_e32 v109, v72, v33
	v_mul_f32_e32 v110, v72, v34
	v_mul_f32_e32 v111, v72, v35
	v_mul_f32_e32 v112, v72, v28
	v_mul_f32_e32 v113, v72, v29
	v_mul_f32_e32 v114, v72, v30
	v_mul_f32_e32 v115, v72, v31
	v_mul_f32_e32 v91, v93, v109
	v_mul_f32_e32 v116, v93, v108
	v_fma_f32 v108, v92, v108, -v91
	v_fma_f32 v109, v92, v109, v116
	v_mul_f32_e32 v91, v95, v111
	v_mul_f32_e32 v116, v95, v110
	v_fma_f32 v110, v94, v110, -v91
	v_fma_f32 v111, v94, v111, v116
	v_mul_f32_e32 v91, v97, v113
	v_mul_f32_e32 v116, v97, v112
	v_fma_f32 v112, v96, v112, -v91
	v_fma_f32 v113, v96, v113, v116
	v_mul_f32_e32 v91, v99, v115
	v_mul_f32_e32 v116, v99, v114
	v_fma_f32 v114, v98, v114, -v91
	v_fma_f32 v115, v98, v115, v116
	v_cvt_pk_bf16_f32 v120, v108, v109
	v_cvt_pk_bf16_f32 v121, v110, v111
	v_cvt_pk_bf16_f32 v122, v112, v113
	v_cvt_pk_bf16_f32 v123, v114, v115
	global_store_dwordx4 v89, v[120:123], s[16:17]
	s_add_u32 s16, s16, 0x4000
	s_addc_u32 s17, s17, 0
	v_mul_f32_e32 v91, v76, v108
	v_mul_f32_e32 v116, v76, v109
	v_cvt_pk_bf16_f32 v124, v91, v116
	v_mul_f32_e32 v91, v76, v110
	v_mul_f32_e32 v116, v76, v111
	v_cvt_pk_bf16_f32 v125, v91, v116
	v_mul_f32_e32 v91, v76, v112
	v_mul_f32_e32 v116, v76, v113
	v_cvt_pk_bf16_f32 v126, v91, v116
	v_mul_f32_e32 v91, v76, v114
	v_mul_f32_e32 v116, v76, v115
	v_cvt_pk_bf16_f32 v127, v91, v116
	ds_write_b128 v84, v[124:127]
	v_mul_f32_e32 v91, v80, v108
	v_mul_f32_e32 v116, v80, v109
	v_cvt_pk_bf16_f32 v128, v91, v116
	v_mul_f32_e32 v91, v80, v110
	v_mul_f32_e32 v116, v80, v111
	v_cvt_pk_bf16_f32 v129, v91, v116
	v_mul_f32_e32 v91, v80, v112
	v_mul_f32_e32 v116, v80, v113
	v_cvt_pk_bf16_f32 v130, v91, v116
	v_mul_f32_e32 v91, v80, v114
	v_mul_f32_e32 v116, v80, v115
	v_cvt_pk_bf16_f32 v131, v91, v116
	s_add_u32 s4, s4, s21
	s_addc_u32 s5, s5, 0
	global_load_dwordx4 v[92:95], v90, s[4:5]
	global_load_dwordx4 v[96:99], v90, s[4:5] offset:16
	s_waitcnt vmcnt(2)
	v_mul_f32_e32 v108, v73, v24
	v_mul_f32_e32 v109, v73, v25
	v_mul_f32_e32 v110, v73, v26
	v_mul_f32_e32 v111, v73, v27
	v_mul_f32_e32 v112, v73, v20
	v_mul_f32_e32 v113, v73, v21
	v_mul_f32_e32 v114, v73, v22
	v_mul_f32_e32 v115, v73, v23
	v_mul_f32_e32 v91, v101, v109
	v_mul_f32_e32 v116, v101, v108
	v_fma_f32 v108, v100, v108, -v91
	v_fma_f32 v109, v100, v109, v116
	v_mul_f32_e32 v91, v103, v111
	v_mul_f32_e32 v116, v103, v110
	v_fma_f32 v110, v102, v110, -v91
	v_fma_f32 v111, v102, v111, v116
	v_mul_f32_e32 v91, v105, v113
	v_mul_f32_e32 v116, v105, v112
	v_fma_f32 v112, v104, v112, -v91
	v_fma_f32 v113, v104, v113, v116
	v_mul_f32_e32 v91, v107, v115
	v_mul_f32_e32 v116, v107, v114
	v_fma_f32 v114, v106, v114, -v91
	v_fma_f32 v115, v106, v115, v116
	v_cvt_pk_bf16_f32 v120, v108, v109
	v_cvt_pk_bf16_f32 v121, v110, v111
	v_cvt_pk_bf16_f32 v122, v112, v113
	v_cvt_pk_bf16_f32 v123, v114, v115
	global_store_dwordx4 v89, v[120:123], s[16:17]
	s_add_u32 s16, s16, 0x4000
	s_addc_u32 s17, s17, 0
	v_mul_f32_e32 v91, v77, v108
	v_mul_f32_e32 v116, v77, v109
	v_cvt_pk_bf16_f32 v124, v91, v116
	v_mul_f32_e32 v91, v77, v110
	v_mul_f32_e32 v116, v77, v111
	v_cvt_pk_bf16_f32 v125, v91, v116
	v_mul_f32_e32 v91, v77, v112
	v_mul_f32_e32 v116, v77, v113
	v_cvt_pk_bf16_f32 v126, v91, v116
	v_mul_f32_e32 v91, v77, v114
	v_mul_f32_e32 v116, v77, v115
	v_cvt_pk_bf16_f32 v127, v91, v116
	ds_write_b128 v84, v[124:127] offset:1024
	v_mul_f32_e32 v91, v81, v108
	v_mul_f32_e32 v116, v81, v109
	v_cvt_pk_bf16_f32 v132, v91, v116
	v_mul_f32_e32 v91, v81, v110
	v_mul_f32_e32 v116, v81, v111
	v_cvt_pk_bf16_f32 v133, v91, v116
	v_mul_f32_e32 v91, v81, v112
	v_mul_f32_e32 v116, v81, v113
	v_cvt_pk_bf16_f32 v134, v91, v116
	v_mul_f32_e32 v91, v81, v114
	v_mul_f32_e32 v116, v81, v115
	v_cvt_pk_bf16_f32 v135, v91, v116
	ds_read_b64_tr_b16 v[120:121], v85
	ds_read_b64_tr_b16 v[122:123], v85 offset:256
	ds_read_b64_tr_b16 v[124:125], v86
	ds_read_b64_tr_b16 v[126:127], v86 offset:256
	s_waitcnt lgkmcnt(0)
	global_store_dwordx4 v87, v[120:123], s[36:37]
	global_store_dwordx4 v88, v[124:127], s[36:37]
	ds_write_b128 v84, v[128:131]
	ds_write_b128 v84, v[132:135] offset:1024
	s_nop 1
	ds_read_b64_tr_b16 v[120:121], v85
	ds_read_b64_tr_b16 v[122:123], v85 offset:256
	ds_read_b64_tr_b16 v[124:125], v86
	ds_read_b64_tr_b16 v[126:127], v86 offset:256
	s_waitcnt lgkmcnt(0)
	global_store_dwordx4 v87, v[120:123], s[40:41]
	global_store_dwordx4 v88, v[124:127], s[40:41]
	s_add_u32 s36, s36, 64
	s_addc_u32 s37, s37, 0
	s_add_u32 s40, s40, 64
	s_addc_u32 s41, s41, 0
	s_add_u32 s4, s4, s21
	s_addc_u32 s5, s5, 0
	global_load_dwordx4 v[100:103], v90, s[4:5]
	global_load_dwordx4 v[104:107], v90, s[4:5] offset:16
	s_waitcnt vmcnt(2)
	v_mul_f32_e32 v108, v74, v16
	v_mul_f32_e32 v109, v74, v17
	v_mul_f32_e32 v110, v74, v18
	v_mul_f32_e32 v111, v74, v19
	v_mul_f32_e32 v112, v74, v12
	v_mul_f32_e32 v113, v74, v13
	v_mul_f32_e32 v114, v74, v14
	v_mul_f32_e32 v115, v74, v15
	v_mul_f32_e32 v91, v93, v109
	v_mul_f32_e32 v116, v93, v108
	v_fma_f32 v108, v92, v108, -v91
	v_fma_f32 v109, v92, v109, v116
	v_mul_f32_e32 v91, v95, v111
	v_mul_f32_e32 v116, v95, v110
	v_fma_f32 v110, v94, v110, -v91
	v_fma_f32 v111, v94, v111, v116
	v_mul_f32_e32 v91, v97, v113
	v_mul_f32_e32 v116, v97, v112
	v_fma_f32 v112, v96, v112, -v91
	v_fma_f32 v113, v96, v113, v116
	v_mul_f32_e32 v91, v99, v115
	v_mul_f32_e32 v116, v99, v114
	v_fma_f32 v114, v98, v114, -v91
	v_fma_f32 v115, v98, v115, v116
	v_cvt_pk_bf16_f32 v120, v108, v109
	v_cvt_pk_bf16_f32 v121, v110, v111
	v_cvt_pk_bf16_f32 v122, v112, v113
	v_cvt_pk_bf16_f32 v123, v114, v115
	global_store_dwordx4 v89, v[120:123], s[16:17]
	s_add_u32 s16, s16, 0x4000
	s_addc_u32 s17, s17, 0
	v_mul_f32_e32 v91, v78, v108
	v_mul_f32_e32 v116, v78, v109
	v_cvt_pk_bf16_f32 v124, v91, v116
	v_mul_f32_e32 v91, v78, v110
	v_mul_f32_e32 v116, v78, v111
	v_cvt_pk_bf16_f32 v125, v91, v116
	v_mul_f32_e32 v91, v78, v112
	v_mul_f32_e32 v116, v78, v113
	v_cvt_pk_bf16_f32 v126, v91, v116
	v_mul_f32_e32 v91, v78, v114
	v_mul_f32_e32 v116, v78, v115
	v_cvt_pk_bf16_f32 v127, v91, v116
	ds_write_b128 v84, v[124:127]
	v_mul_f32_e32 v91, v82, v108
	v_mul_f32_e32 v116, v82, v109
	v_cvt_pk_bf16_f32 v128, v91, v116
	v_mul_f32_e32 v91, v82, v110
	v_mul_f32_e32 v116, v82, v111
	v_cvt_pk_bf16_f32 v129, v91, v116
	v_mul_f32_e32 v91, v82, v112
	v_mul_f32_e32 v116, v82, v113
	v_cvt_pk_bf16_f32 v130, v91, v116
	v_mul_f32_e32 v91, v82, v114
	v_mul_f32_e32 v116, v82, v115
	v_cvt_pk_bf16_f32 v131, v91, v116
	s_waitcnt vmcnt(0)
	v_mul_f32_e32 v108, v75, v8
	v_mul_f32_e32 v109, v75, v9
	v_mul_f32_e32 v110, v75, v10
	v_mul_f32_e32 v111, v75, v11
	v_mul_f32_e32 v112, v75, v4
	v_mul_f32_e32 v113, v75, v5
	v_mul_f32_e32 v114, v75, v6
	v_mul_f32_e32 v115, v75, v7
	v_mul_f32_e32 v91, v101, v109
	v_mul_f32_e32 v116, v101, v108
	v_fma_f32 v108, v100, v108, -v91
	v_fma_f32 v109, v100, v109, v116
	v_mul_f32_e32 v91, v103, v111
	v_mul_f32_e32 v116, v103, v110
	v_fma_f32 v110, v102, v110, -v91
	v_fma_f32 v111, v102, v111, v116
	v_mul_f32_e32 v91, v105, v113
	v_mul_f32_e32 v116, v105, v112
	v_fma_f32 v112, v104, v112, -v91
	v_fma_f32 v113, v104, v113, v116
	v_mul_f32_e32 v91, v107, v115
	v_mul_f32_e32 v116, v107, v114
	v_fma_f32 v114, v106, v114, -v91
	v_fma_f32 v115, v106, v115, v116
	v_cvt_pk_bf16_f32 v120, v108, v109
	v_cvt_pk_bf16_f32 v121, v110, v111
	v_cvt_pk_bf16_f32 v122, v112, v113
	v_cvt_pk_bf16_f32 v123, v114, v115
	global_store_dwordx4 v89, v[120:123], s[16:17]
	s_add_u32 s16, s16, 0x14000
	s_addc_u32 s17, s17, 0
	v_mul_f32_e32 v91, v79, v108
	v_mul_f32_e32 v116, v79, v109
	v_cvt_pk_bf16_f32 v124, v91, v116
	v_mul_f32_e32 v91, v79, v110
	v_mul_f32_e32 v116, v79, v111
	v_cvt_pk_bf16_f32 v125, v91, v116
	v_mul_f32_e32 v91, v79, v112
	v_mul_f32_e32 v116, v79, v113
	v_cvt_pk_bf16_f32 v126, v91, v116
	v_mul_f32_e32 v91, v79, v114
	v_mul_f32_e32 v116, v79, v115
	v_cvt_pk_bf16_f32 v127, v91, v116
	ds_write_b128 v84, v[124:127] offset:1024
	v_mul_f32_e32 v91, v83, v108
	v_mul_f32_e32 v116, v83, v109
	v_cvt_pk_bf16_f32 v132, v91, v116
	v_mul_f32_e32 v91, v83, v110
	v_mul_f32_e32 v116, v83, v111
	v_cvt_pk_bf16_f32 v133, v91, v116
	v_mul_f32_e32 v91, v83, v112
	v_mul_f32_e32 v116, v83, v113
	v_cvt_pk_bf16_f32 v134, v91, v116
	v_mul_f32_e32 v91, v83, v114
	v_mul_f32_e32 v116, v83, v115
	v_cvt_pk_bf16_f32 v135, v91, v116
	ds_read_b64_tr_b16 v[120:121], v85
	ds_read_b64_tr_b16 v[122:123], v85 offset:256
	ds_read_b64_tr_b16 v[124:125], v86
	ds_read_b64_tr_b16 v[126:127], v86 offset:256
	s_waitcnt lgkmcnt(0)
	global_store_dwordx4 v87, v[120:123], s[36:37]
	global_store_dwordx4 v88, v[124:127], s[36:37]
	ds_write_b128 v84, v[128:131]
	ds_write_b128 v84, v[132:135] offset:1024
	s_nop 1
	ds_read_b64_tr_b16 v[120:121], v85
	ds_read_b64_tr_b16 v[122:123], v85 offset:256
	ds_read_b64_tr_b16 v[124:125], v86
	ds_read_b64_tr_b16 v[126:127], v86 offset:256
	s_waitcnt lgkmcnt(0)
	global_store_dwordx4 v87, v[120:123], s[40:41]
	global_store_dwordx4 v88, v[124:127], s[40:41]
.Lsec1_b_done:
.LBB0_238:
	s_mov_b64 s[0:1], 0
.LBB0_239:
	s_andn2_b64 vcc, exec, s[0:1]
	s_cbranch_vccnz .LBB0_45
	s_lshl_b32 s0, s48, 8
	v_add_u32_e32 v92, s0, v241
	s_movk_i32 s0, 0x7cf
	v_cmp_gt_i32_e32 vcc, s20, v92
	v_and_or_b32 v2, v92, s0, 16
	v_ashrrev_i32_e32 v93, 31, v92
	v_cndmask_b32_e32 v2, v181, v2, vcc
	v_lshl_add_u64 v[68:69], v[92:93], 2, s[70:71]
	v_lshlrev_b32_e32 v2, 8, v2
	global_load_dword v114, v[68:69], off
	v_lshl_add_u64 v[70:71], v[182:183], 0, v[2:3]
	global_load_dwordx4 v[106:109], v[70:71], off offset:16
	global_load_dwordx4 v[110:113], v[70:71], off
	s_movk_i32 s0, 0x7df
	v_or_b32_e32 v98, 16, v92
	v_bitop3_b32 v2, v92, s0, 16 bitop3:0xc8
	v_cmp_gt_i32_e32 vcc, s20, v98
	v_add_u32_e32 v2, 16, v2
	global_load_dword v104, v[68:69], off offset:64
	v_cndmask_b32_e32 v2, v181, v2, vcc
	v_lshlrev_b32_e32 v2, 8, v2
	v_lshl_add_u64 v[70:71], v[182:183], 0, v[2:3]
	global_load_dwordx4 v[84:87], v[70:71], off offset:16
	global_load_dwordx4 v[88:91], v[70:71], off
	v_or_b32_e32 v100, 32, v92
	s_movk_i32 s0, 0x7ef
	v_cmp_gt_i32_e32 vcc, s20, v100
	v_and_or_b32 v2, v100, s0, 16
	global_load_dword v102, v[68:69], off offset:128
	v_cndmask_b32_e32 v2, v181, v2, vcc
	v_lshlrev_b32_e32 v2, 8, v2
	v_lshl_add_u64 v[70:71], v[182:183], 0, v[2:3]
	global_load_dwordx4 v[76:79], v[70:71], off offset:16
	global_load_dwordx4 v[80:83], v[70:71], off
	s_movk_i32 s0, 0x7ff
	v_or_b32_e32 v94, 48, v92
	v_bitop3_b32 v2, v92, s0, 48 bitop3:0xc8
	v_cmp_gt_i32_e32 vcc, s20, v94
	v_add_u32_e32 v2, 16, v2
	global_load_dword v96, v[68:69], off offset:192
	v_cndmask_b32_e32 v2, v181, v2, vcc
	v_lshlrev_b32_e32 v2, 8, v2
	v_lshl_add_u64 v[72:73], v[182:183], 0, v[2:3]
	global_load_dwordx4 v[68:71], v[72:73], off offset:16
	s_nop 0
	global_load_dwordx4 v[72:75], v[72:73], off
	s_mov_b32 s0, 0x3e000000
	s_ashr_i32 s75, s74, 31
	v_ashrrev_i32_e32 v99, 31, v98
	v_ashrrev_i32_e32 v101, 31, v100
	v_ashrrev_i32_e32 v95, 31, v94
	s_cmp_eq_u32 s48, 64
	s_waitcnt vmcnt(0)
	v_pk_mul_f32 v[64:65], v[64:65], v[114:115] op_sel_hi:[1,0]
	v_pk_mul_f32 v[66:67], v[66:67], v[114:115] op_sel_hi:[1,0]
	v_pk_mul_f32 v[116:117], v[110:111], v[64:65] op_sel:[1,1] op_sel_hi:[1,0]
	v_mov_b32_e32 v2, v113
	v_pk_fma_f32 v[118:119], v[110:111], v[64:65], v[116:117] op_sel_hi:[0,1,1] neg_lo:[0,0,1] neg_hi:[0,0,1]
	v_pk_fma_f32 v[110:111], v[110:111], v[64:65], v[116:117] op_sel_hi:[0,1,1]
	v_pk_mul_f32 v[60:61], v[60:61], v[114:115] op_sel_hi:[1,0]
	v_pk_mul_f32 v[64:65], v[2:3], v[66:67] op_sel:[0,1] op_sel_hi:[0,0]
	v_mov_b32_e32 v119, v111
	v_pk_mul_f32 v[62:63], v[62:63], v[114:115] op_sel_hi:[1,0]
	v_pk_mul_f32 v[110:111], v[106:107], v[60:61] op_sel:[1,1] op_sel_hi:[1,0]
	v_mov_b32_e32 v2, v109
	v_pk_fma_f32 v[116:117], v[112:113], v[66:67], v[64:65] op_sel_hi:[0,1,1] neg_lo:[0,0,1] neg_hi:[0,0,1]
	v_pk_fma_f32 v[64:65], v[112:113], v[66:67], v[64:65] op_sel_hi:[0,1,1]
	v_pk_fma_f32 v[112:113], v[106:107], v[60:61], v[110:111] op_sel_hi:[0,1,1] neg_lo:[0,0,1] neg_hi:[0,0,1]
	v_pk_fma_f32 v[60:61], v[106:107], v[60:61], v[110:111] op_sel_hi:[0,1,1]
	v_pk_mul_f32 v[106:107], v[2:3], v[62:63] op_sel:[0,1] op_sel_hi:[0,0]
	v_pk_fma_f32 v[110:111], v[108:109], v[62:63], v[106:107] op_sel_hi:[0,1,1] neg_lo:[0,0,1] neg_hi:[0,0,1]
	v_pk_fma_f32 v[62:63], v[108:109], v[62:63], v[106:107] op_sel_hi:[0,1,1]
	v_mov_b32_e32 v111, v63
	v_mov_b32_e32 v113, v61
	v_lshlrev_b64 v[60:61], 10, v[92:93]
	v_mov_b32_e32 v117, v65
	v_pk_mul_f32 v[62:63], v[110:111], s[0:1] op_sel_hi:[1,0]
	v_lshl_add_u64 v[108:109], s[94:95], 0, v[60:61]
	v_lshl_add_u64 v[60:61], s[74:75], 0, v[178:179]
	v_pk_mul_f32 v[56:57], v[56:57], v[104:105] op_sel_hi:[1,0]
	v_pk_mul_f32 v[64:65], v[116:117], s[0:1] op_sel_hi:[1,0]
	v_lshlrev_b64 v[60:61], 1, v[60:61]
	v_cvt_pk_bf16_f32 v111, v62, v63
	v_pk_mul_f32 v[58:59], v[58:59], v[104:105] op_sel_hi:[1,0]
	v_pk_mul_f32 v[62:63], v[88:89], v[56:57] op_sel:[1,1] op_sel_hi:[1,0]
	v_mov_b32_e32 v2, v91
	v_pk_mul_f32 v[66:67], v[118:119], s[0:1] op_sel_hi:[1,0]
	v_pk_mul_f32 v[106:107], v[112:113], s[0:1] op_sel_hi:[1,0]
	v_lshl_add_u64 v[112:113], v[108:109], 0, v[60:61]
	v_cvt_pk_bf16_f32 v109, v64, v65
	v_pk_fma_f32 v[64:65], v[88:89], v[56:57], v[62:63] op_sel_hi:[0,1,1] neg_lo:[0,0,1] neg_hi:[0,0,1]
	v_pk_fma_f32 v[56:57], v[88:89], v[56:57], v[62:63] op_sel_hi:[0,1,1]
	v_pk_mul_f32 v[62:63], v[2:3], v[58:59] op_sel:[0,1] op_sel_hi:[0,0]
	v_pk_mul_f32 v[52:53], v[52:53], v[104:105] op_sel_hi:[1,0]
	v_cvt_pk_bf16_f32 v108, v66, v67
	v_pk_fma_f32 v[66:67], v[90:91], v[58:59], v[62:63] op_sel_hi:[0,1,1] neg_lo:[0,0,1] neg_hi:[0,0,1]
	v_pk_fma_f32 v[58:59], v[90:91], v[58:59], v[62:63] op_sel_hi:[0,1,1]
	v_mov_b32_e32 v65, v57
	v_pk_mul_f32 v[54:55], v[54:55], v[104:105] op_sel_hi:[1,0]
	v_pk_mul_f32 v[62:63], v[84:85], v[52:53] op_sel:[1,1] op_sel_hi:[1,0]
	v_mov_b32_e32 v2, v87
	v_mov_b32_e32 v67, v59
	v_pk_mul_f32 v[56:57], v[64:65], s[0:1] op_sel_hi:[1,0]
	v_pk_fma_f32 v[64:65], v[84:85], v[52:53], v[62:63] op_sel_hi:[0,1,1] neg_lo:[0,0,1] neg_hi:[0,0,1]
	v_pk_fma_f32 v[52:53], v[84:85], v[52:53], v[62:63] op_sel_hi:[0,1,1]
	v_pk_mul_f32 v[62:63], v[2:3], v[54:55] op_sel:[0,1] op_sel_hi:[0,0]
	v_pk_mul_f32 v[58:59], v[66:67], s[0:1] op_sel_hi:[1,0]
	v_pk_fma_f32 v[66:67], v[86:87], v[54:55], v[62:63] op_sel_hi:[0,1,1] neg_lo:[0,0,1] neg_hi:[0,0,1]
	v_pk_fma_f32 v[54:55], v[86:87], v[54:55], v[62:63] op_sel_hi:[0,1,1]
	v_mov_b32_e32 v67, v55
	v_mov_b32_e32 v65, v53
	v_lshlrev_b64 v[52:53], 10, v[98:99]
	v_pk_mul_f32 v[62:63], v[66:67], s[0:1] op_sel_hi:[1,0]
	v_pk_mul_f32 v[54:55], v[64:65], s[0:1] op_sel_hi:[1,0]
	v_lshl_add_u64 v[52:53], s[94:95], 0, v[52:53]
	v_lshl_add_u64 v[64:65], v[52:53], 0, v[60:61]
	v_cvt_pk_bf16_f32 v52, v56, v57
	v_cvt_pk_bf16_f32 v53, v58, v59
	v_cvt_pk_bf16_f32 v54, v54, v55
	v_cvt_pk_bf16_f32 v55, v62, v63
	v_pk_mul_f32 v[48:49], v[48:49], v[102:103] op_sel_hi:[1,0]
	global_store_dwordx4 v[64:65], v[52:55], off offset:256
	v_pk_mul_f32 v[50:51], v[50:51], v[102:103] op_sel_hi:[1,0]
	v_mov_b32_e32 v2, v83
	v_pk_mul_f32 v[52:53], v[80:81], v[48:49] op_sel:[1,1] op_sel_hi:[1,0]
	v_pk_mul_f32 v[44:45], v[44:45], v[102:103] op_sel_hi:[1,0]
	v_pk_fma_f32 v[54:55], v[80:81], v[48:49], v[52:53] op_sel_hi:[0,1,1] neg_lo:[0,0,1] neg_hi:[0,0,1]
	v_pk_fma_f32 v[48:49], v[80:81], v[48:49], v[52:53] op_sel_hi:[0,1,1]
	v_pk_mul_f32 v[52:53], v[2:3], v[50:51] op_sel:[0,1] op_sel_hi:[0,0]
	v_pk_fma_f32 v[56:57], v[82:83], v[50:51], v[52:53] op_sel_hi:[0,1,1] neg_lo:[0,0,1] neg_hi:[0,0,1]
	v_pk_fma_f32 v[50:51], v[82:83], v[50:51], v[52:53] op_sel_hi:[0,1,1]
	v_mov_b32_e32 v55, v49
	v_pk_mul_f32 v[46:47], v[46:47], v[102:103] op_sel_hi:[1,0]
	v_pk_mul_f32 v[52:53], v[76:77], v[44:45] op_sel:[1,1] op_sel_hi:[1,0]
	v_mov_b32_e32 v2, v79
	v_mov_b32_e32 v57, v51
	v_pk_mul_f32 v[48:49], v[54:55], s[0:1] op_sel_hi:[1,0]
	v_pk_fma_f32 v[54:55], v[76:77], v[44:45], v[52:53] op_sel_hi:[0,1,1] neg_lo:[0,0,1] neg_hi:[0,0,1]
	v_pk_fma_f32 v[44:45], v[76:77], v[44:45], v[52:53] op_sel_hi:[0,1,1]
	v_pk_mul_f32 v[52:53], v[2:3], v[46:47] op_sel:[0,1] op_sel_hi:[0,0]
	v_pk_mul_f32 v[50:51], v[56:57], s[0:1] op_sel_hi:[1,0]
	v_pk_fma_f32 v[56:57], v[78:79], v[46:47], v[52:53] op_sel_hi:[0,1,1] neg_lo:[0,0,1] neg_hi:[0,0,1]
	v_pk_fma_f32 v[46:47], v[78:79], v[46:47], v[52:53] op_sel_hi:[0,1,1]
	v_mov_b32_e32 v57, v47
	v_mov_b32_e32 v55, v45
	v_lshlrev_b64 v[44:45], 10, v[100:101]
	v_pk_mul_f32 v[52:53], v[56:57], s[0:1] op_sel_hi:[1,0]
	v_pk_mul_f32 v[46:47], v[54:55], s[0:1] op_sel_hi:[1,0]
	v_lshl_add_u64 v[44:45], s[94:95], 0, v[44:45]
	v_lshl_add_u64 v[54:55], v[44:45], 0, v[60:61]
	v_cvt_pk_bf16_f32 v44, v48, v49
	v_cvt_pk_bf16_f32 v45, v50, v51
	v_cvt_pk_bf16_f32 v46, v46, v47
	v_cvt_pk_bf16_f32 v47, v52, v53
	v_pk_mul_f32 v[40:41], v[40:41], v[96:97] op_sel_hi:[1,0]
	global_store_dwordx4 v[54:55], v[44:47], off offset:256
	v_pk_mul_f32 v[42:43], v[42:43], v[96:97] op_sel_hi:[1,0]
	v_mov_b32_e32 v2, v75
	v_pk_mul_f32 v[44:45], v[72:73], v[40:41] op_sel:[1,1] op_sel_hi:[1,0]
	v_pk_mul_f32 v[36:37], v[36:37], v[96:97] op_sel_hi:[1,0]
	v_pk_fma_f32 v[46:47], v[72:73], v[40:41], v[44:45] op_sel_hi:[0,1,1] neg_lo:[0,0,1] neg_hi:[0,0,1]
	v_pk_fma_f32 v[40:41], v[72:73], v[40:41], v[44:45] op_sel_hi:[0,1,1]
	v_pk_mul_f32 v[44:45], v[2:3], v[42:43] op_sel:[0,1] op_sel_hi:[0,0]
	v_pk_fma_f32 v[48:49], v[74:75], v[42:43], v[44:45] op_sel_hi:[0,1,1] neg_lo:[0,0,1] neg_hi:[0,0,1]
	v_pk_fma_f32 v[42:43], v[74:75], v[42:43], v[44:45] op_sel_hi:[0,1,1]
	v_mov_b32_e32 v47, v41
	v_pk_mul_f32 v[38:39], v[38:39], v[96:97] op_sel_hi:[1,0]
	v_pk_mul_f32 v[44:45], v[68:69], v[36:37] op_sel:[1,1] op_sel_hi:[1,0]
	v_mov_b32_e32 v2, v71
	v_mov_b32_e32 v49, v43
	v_pk_mul_f32 v[40:41], v[46:47], s[0:1] op_sel_hi:[1,0]
	v_pk_fma_f32 v[46:47], v[68:69], v[36:37], v[44:45] op_sel_hi:[0,1,1] neg_lo:[0,0,1] neg_hi:[0,0,1]
	v_pk_fma_f32 v[36:37], v[68:69], v[36:37], v[44:45] op_sel_hi:[0,1,1]
	v_pk_mul_f32 v[44:45], v[2:3], v[38:39] op_sel:[0,1] op_sel_hi:[0,0]
	v_pk_mul_f32 v[42:43], v[48:49], s[0:1] op_sel_hi:[1,0]
	v_pk_fma_f32 v[48:49], v[70:71], v[38:39], v[44:45] op_sel_hi:[0,1,1] neg_lo:[0,0,1] neg_hi:[0,0,1]
	v_pk_fma_f32 v[38:39], v[70:71], v[38:39], v[44:45] op_sel_hi:[0,1,1]
	v_mov_b32_e32 v49, v39
	v_mov_b32_e32 v47, v37
	v_lshlrev_b64 v[36:37], 10, v[94:95]
	v_pk_mul_f32 v[44:45], v[48:49], s[0:1] op_sel_hi:[1,0]
	v_pk_mul_f32 v[38:39], v[46:47], s[0:1] op_sel_hi:[1,0]
	v_lshl_add_u64 v[36:37], s[94:95], 0, v[36:37]
	v_cvt_pk_bf16_f32 v110, v106, v107
	v_lshl_add_u64 v[46:47], v[36:37], 0, v[60:61]
	v_cvt_pk_bf16_f32 v36, v40, v41
	v_cvt_pk_bf16_f32 v37, v42, v43
	v_cvt_pk_bf16_f32 v38, v38, v39
	v_cvt_pk_bf16_f32 v39, v44, v45
	global_store_dwordx4 v[112:113], v[108:111], off offset:256
	global_store_dwordx4 v[46:47], v[36:39], off offset:256
	s_cbranch_scc1 .LBB0_45
	v_add_u32_e32 v74, 0x80, v92
	s_movk_i32 s0, 0x7cf
	v_cmp_gt_i32_e32 vcc, s20, v74
	v_and_or_b32 v2, v74, s0, 16
	v_ashrrev_i32_e32 v75, 31, v74
	v_cndmask_b32_e32 v2, v181, v2, vcc
	v_lshl_add_u64 v[48:49], v[74:75], 2, s[70:71]
	v_lshlrev_b32_e32 v2, 8, v2
	global_load_dword v84, v[48:49], off
	v_lshl_add_u64 v[36:37], v[182:183], 0, v[2:3]
	global_load_dwordx4 v[76:79], v[36:37], off offset:16
	global_load_dwordx4 v[80:83], v[36:37], off
	v_add_u32_e32 v62, 0x90, v92
	v_and_b32_e32 v2, 0x7df, v62
	v_cmp_gt_i32_e32 vcc, s20, v62
	v_add_u32_e32 v2, 16, v2
	global_load_dword v72, v[48:49], off offset:64
	v_cndmask_b32_e32 v2, v181, v2, vcc
	v_lshlrev_b32_e32 v2, 8, v2
	v_lshl_add_u64 v[36:37], v[182:183], 0, v[2:3]
	global_load_dwordx4 v[44:47], v[36:37], off offset:16
	global_load_dwordx4 v[56:59], v[36:37], off
	v_add_u32_e32 v64, 0xa0, v92
	s_movk_i32 s0, 0x7ef
	v_cmp_gt_i32_e32 vcc, s20, v64
	v_and_or_b32 v2, v64, s0, 16
	global_load_dword v68, v[48:49], off offset:128
	v_cndmask_b32_e32 v2, v181, v2, vcc
	v_lshlrev_b32_e32 v2, 8, v2
	v_lshl_add_u64 v[40:41], v[182:183], 0, v[2:3]
	global_load_dwordx4 v[36:39], v[40:41], off offset:16
	s_nop 0
	global_load_dwordx4 v[40:43], v[40:41], off
	v_add_u32_e32 v66, 0xb0, v92
	v_and_b32_e32 v2, 0x7ff, v66
	v_cmp_gt_i32_e32 vcc, s20, v66
	v_add_u32_e32 v2, 16, v2
	global_load_dword v70, v[48:49], off offset:192
	v_cndmask_b32_e32 v2, v181, v2, vcc
	v_lshlrev_b32_e32 v2, 8, v2
	v_lshl_add_u64 v[52:53], v[182:183], 0, v[2:3]
	global_load_dwordx4 v[48:51], v[52:53], off offset:16
	s_nop 0
	global_load_dwordx4 v[52:55], v[52:53], off
	s_mov_b32 s0, 0x3e000000
	v_ashrrev_i32_e32 v63, 31, v62
	v_ashrrev_i32_e32 v65, 31, v64
	v_ashrrev_i32_e32 v67, 31, v66
	s_waitcnt vmcnt(0)
	v_pk_mul_f32 v[32:33], v[32:33], v[84:85] op_sel_hi:[1,0]
	v_pk_mul_f32 v[34:35], v[34:35], v[84:85] op_sel_hi:[1,0]
	v_pk_mul_f32 v[86:87], v[80:81], v[32:33] op_sel:[1,1] op_sel_hi:[1,0]
	v_mov_b32_e32 v2, v83
	v_pk_fma_f32 v[88:89], v[80:81], v[32:33], v[86:87] op_sel_hi:[0,1,1] neg_lo:[0,0,1] neg_hi:[0,0,1]
	v_pk_fma_f32 v[32:33], v[80:81], v[32:33], v[86:87] op_sel_hi:[0,1,1]
	v_pk_mul_f32 v[80:81], v[2:3], v[34:35] op_sel:[0,1] op_sel_hi:[0,0]
	v_pk_mul_f32 v[28:29], v[28:29], v[84:85] op_sel_hi:[1,0]
	v_pk_fma_f32 v[86:87], v[82:83], v[34:35], v[80:81] op_sel_hi:[0,1,1] neg_lo:[0,0,1] neg_hi:[0,0,1]
	v_pk_fma_f32 v[34:35], v[82:83], v[34:35], v[80:81] op_sel_hi:[0,1,1]
	v_pk_mul_f32 v[30:31], v[30:31], v[84:85] op_sel_hi:[1,0]
	v_pk_mul_f32 v[80:81], v[76:77], v[28:29] op_sel:[1,1] op_sel_hi:[1,0]
	v_mov_b32_e32 v2, v79
	v_pk_fma_f32 v[82:83], v[76:77], v[28:29], v[80:81] op_sel_hi:[0,1,1] neg_lo:[0,0,1] neg_hi:[0,0,1]
	v_pk_fma_f32 v[28:29], v[76:77], v[28:29], v[80:81] op_sel_hi:[0,1,1]
	v_pk_mul_f32 v[76:77], v[2:3], v[30:31] op_sel:[0,1] op_sel_hi:[0,0]
	v_pk_fma_f32 v[80:81], v[78:79], v[30:31], v[76:77] op_sel_hi:[0,1,1] neg_lo:[0,0,1] neg_hi:[0,0,1]
	v_pk_fma_f32 v[30:31], v[78:79], v[30:31], v[76:77] op_sel_hi:[0,1,1]
	v_mov_b32_e32 v87, v35
	v_mov_b32_e32 v89, v33
	v_mov_b32_e32 v81, v31
	v_mov_b32_e32 v83, v29
	v_lshlrev_b64 v[28:29], 10, v[74:75]
	v_pk_mul_f32 v[34:35], v[86:87], s[0:1] op_sel_hi:[1,0]
	v_pk_mul_f32 v[32:33], v[88:89], s[0:1] op_sel_hi:[1,0]
	v_pk_mul_f32 v[76:77], v[80:81], s[0:1] op_sel_hi:[1,0]
	v_pk_mul_f32 v[30:31], v[82:83], s[0:1] op_sel_hi:[1,0]
	v_lshl_add_u64 v[28:29], s[94:95], 0, v[28:29]
	v_lshl_add_u64 v[74:75], v[28:29], 0, v[60:61]
	v_cvt_pk_bf16_f32 v28, v32, v33
	v_cvt_pk_bf16_f32 v29, v34, v35
	v_cvt_pk_bf16_f32 v30, v30, v31
	v_cvt_pk_bf16_f32 v31, v76, v77
	v_pk_mul_f32 v[24:25], v[24:25], v[72:73] op_sel_hi:[1,0]
	global_store_dwordx4 v[74:75], v[28:31], off offset:256
	v_pk_mul_f32 v[26:27], v[26:27], v[72:73] op_sel_hi:[1,0]
	v_mov_b32_e32 v2, v59
	v_pk_mul_f32 v[28:29], v[56:57], v[24:25] op_sel:[1,1] op_sel_hi:[1,0]
	v_pk_mul_f32 v[20:21], v[20:21], v[72:73] op_sel_hi:[1,0]
	v_pk_fma_f32 v[30:31], v[56:57], v[24:25], v[28:29] op_sel_hi:[0,1,1] neg_lo:[0,0,1] neg_hi:[0,0,1]
	v_pk_fma_f32 v[24:25], v[56:57], v[24:25], v[28:29] op_sel_hi:[0,1,1]
	v_pk_mul_f32 v[28:29], v[2:3], v[26:27] op_sel:[0,1] op_sel_hi:[0,0]
	v_pk_fma_f32 v[32:33], v[58:59], v[26:27], v[28:29] op_sel_hi:[0,1,1] neg_lo:[0,0,1] neg_hi:[0,0,1]
	v_pk_fma_f32 v[26:27], v[58:59], v[26:27], v[28:29] op_sel_hi:[0,1,1]
	v_mov_b32_e32 v31, v25
	v_pk_mul_f32 v[22:23], v[22:23], v[72:73] op_sel_hi:[1,0]
	v_pk_mul_f32 v[28:29], v[44:45], v[20:21] op_sel:[1,1] op_sel_hi:[1,0]
	v_mov_b32_e32 v2, v47
	v_mov_b32_e32 v33, v27
	v_pk_mul_f32 v[24:25], v[30:31], s[0:1] op_sel_hi:[1,0]
	v_pk_fma_f32 v[30:31], v[44:45], v[20:21], v[28:29] op_sel_hi:[0,1,1] neg_lo:[0,0,1] neg_hi:[0,0,1]
	v_pk_fma_f32 v[20:21], v[44:45], v[20:21], v[28:29] op_sel_hi:[0,1,1]
	v_pk_mul_f32 v[28:29], v[2:3], v[22:23] op_sel:[0,1] op_sel_hi:[0,0]
	v_pk_mul_f32 v[26:27], v[32:33], s[0:1] op_sel_hi:[1,0]
	v_pk_fma_f32 v[32:33], v[46:47], v[22:23], v[28:29] op_sel_hi:[0,1,1] neg_lo:[0,0,1] neg_hi:[0,0,1]
	v_pk_fma_f32 v[22:23], v[46:47], v[22:23], v[28:29] op_sel_hi:[0,1,1]
	v_mov_b32_e32 v33, v23
	v_mov_b32_e32 v31, v21
	v_lshlrev_b64 v[20:21], 10, v[62:63]
	v_pk_mul_f32 v[28:29], v[32:33], s[0:1] op_sel_hi:[1,0]
	v_pk_mul_f32 v[22:23], v[30:31], s[0:1] op_sel_hi:[1,0]
	v_lshl_add_u64 v[20:21], s[94:95], 0, v[20:21]
	v_lshl_add_u64 v[30:31], v[20:21], 0, v[60:61]
	v_cvt_pk_bf16_f32 v20, v24, v25
	v_cvt_pk_bf16_f32 v21, v26, v27
	v_cvt_pk_bf16_f32 v22, v22, v23
	v_cvt_pk_bf16_f32 v23, v28, v29
	v_pk_mul_f32 v[16:17], v[16:17], v[68:69] op_sel_hi:[1,0]
	global_store_dwordx4 v[30:31], v[20:23], off offset:256
	v_pk_mul_f32 v[18:19], v[18:19], v[68:69] op_sel_hi:[1,0]
	v_mov_b32_e32 v2, v43
	v_pk_mul_f32 v[20:21], v[40:41], v[16:17] op_sel:[1,1] op_sel_hi:[1,0]
	v_pk_mul_f32 v[12:13], v[12:13], v[68:69] op_sel_hi:[1,0]
	v_pk_fma_f32 v[22:23], v[40:41], v[16:17], v[20:21] op_sel_hi:[0,1,1] neg_lo:[0,0,1] neg_hi:[0,0,1]
	v_pk_fma_f32 v[16:17], v[40:41], v[16:17], v[20:21] op_sel_hi:[0,1,1]
	v_pk_mul_f32 v[20:21], v[2:3], v[18:19] op_sel:[0,1] op_sel_hi:[0,0]
	v_pk_fma_f32 v[24:25], v[42:43], v[18:19], v[20:21] op_sel_hi:[0,1,1] neg_lo:[0,0,1] neg_hi:[0,0,1]
	v_pk_fma_f32 v[18:19], v[42:43], v[18:19], v[20:21] op_sel_hi:[0,1,1]
	v_mov_b32_e32 v23, v17
	v_pk_mul_f32 v[14:15], v[14:15], v[68:69] op_sel_hi:[1,0]
	v_pk_mul_f32 v[20:21], v[36:37], v[12:13] op_sel:[1,1] op_sel_hi:[1,0]
	v_mov_b32_e32 v2, v39
	v_mov_b32_e32 v25, v19
	v_pk_mul_f32 v[16:17], v[22:23], s[0:1] op_sel_hi:[1,0]
	v_pk_fma_f32 v[22:23], v[36:37], v[12:13], v[20:21] op_sel_hi:[0,1,1] neg_lo:[0,0,1] neg_hi:[0,0,1]
	v_pk_fma_f32 v[12:13], v[36:37], v[12:13], v[20:21] op_sel_hi:[0,1,1]
	v_pk_mul_f32 v[20:21], v[2:3], v[14:15] op_sel:[0,1] op_sel_hi:[0,0]
	v_pk_mul_f32 v[18:19], v[24:25], s[0:1] op_sel_hi:[1,0]
	v_pk_fma_f32 v[24:25], v[38:39], v[14:15], v[20:21] op_sel_hi:[0,1,1] neg_lo:[0,0,1] neg_hi:[0,0,1]
	v_pk_fma_f32 v[14:15], v[38:39], v[14:15], v[20:21] op_sel_hi:[0,1,1]
	v_mov_b32_e32 v25, v15
	v_mov_b32_e32 v23, v13
	v_lshlrev_b64 v[12:13], 10, v[64:65]
	v_pk_mul_f32 v[20:21], v[24:25], s[0:1] op_sel_hi:[1,0]
	v_pk_mul_f32 v[14:15], v[22:23], s[0:1] op_sel_hi:[1,0]
	v_lshl_add_u64 v[12:13], s[94:95], 0, v[12:13]
	v_lshl_add_u64 v[22:23], v[12:13], 0, v[60:61]
	v_cvt_pk_bf16_f32 v12, v16, v17
	v_cvt_pk_bf16_f32 v13, v18, v19
	v_cvt_pk_bf16_f32 v14, v14, v15
	v_cvt_pk_bf16_f32 v15, v20, v21
	v_pk_mul_f32 v[8:9], v[8:9], v[70:71] op_sel_hi:[1,0]
	global_store_dwordx4 v[22:23], v[12:15], off offset:256
	v_pk_mul_f32 v[10:11], v[10:11], v[70:71] op_sel_hi:[1,0]
	v_mov_b32_e32 v2, v55
	v_pk_mul_f32 v[12:13], v[52:53], v[8:9] op_sel:[1,1] op_sel_hi:[1,0]
	v_pk_mul_f32 v[4:5], v[4:5], v[70:71] op_sel_hi:[1,0]
	v_pk_fma_f32 v[14:15], v[52:53], v[8:9], v[12:13] op_sel_hi:[0,1,1] neg_lo:[0,0,1] neg_hi:[0,0,1]
	v_pk_fma_f32 v[8:9], v[52:53], v[8:9], v[12:13] op_sel_hi:[0,1,1]
	v_pk_mul_f32 v[12:13], v[2:3], v[10:11] op_sel:[0,1] op_sel_hi:[0,0]
	v_pk_fma_f32 v[16:17], v[54:55], v[10:11], v[12:13] op_sel_hi:[0,1,1] neg_lo:[0,0,1] neg_hi:[0,0,1]
	v_pk_fma_f32 v[10:11], v[54:55], v[10:11], v[12:13] op_sel_hi:[0,1,1]
	v_mov_b32_e32 v15, v9
	v_pk_mul_f32 v[6:7], v[6:7], v[70:71] op_sel_hi:[1,0]
	v_pk_mul_f32 v[12:13], v[48:49], v[4:5] op_sel:[1,1] op_sel_hi:[1,0]
	v_mov_b32_e32 v2, v51
	v_mov_b32_e32 v17, v11
	v_pk_mul_f32 v[8:9], v[14:15], s[0:1] op_sel_hi:[1,0]
	v_pk_fma_f32 v[14:15], v[48:49], v[4:5], v[12:13] op_sel_hi:[0,1,1] neg_lo:[0,0,1] neg_hi:[0,0,1]
	v_pk_fma_f32 v[4:5], v[48:49], v[4:5], v[12:13] op_sel_hi:[0,1,1]
	v_pk_mul_f32 v[12:13], v[2:3], v[6:7] op_sel:[0,1] op_sel_hi:[0,0]
	v_pk_mul_f32 v[10:11], v[16:17], s[0:1] op_sel_hi:[1,0]
	v_pk_fma_f32 v[16:17], v[50:51], v[6:7], v[12:13] op_sel_hi:[0,1,1] neg_lo:[0,0,1] neg_hi:[0,0,1]
	v_pk_fma_f32 v[6:7], v[50:51], v[6:7], v[12:13] op_sel_hi:[0,1,1]
	v_mov_b32_e32 v17, v7
	v_mov_b32_e32 v15, v5
	v_lshlrev_b64 v[4:5], 10, v[66:67]
	v_pk_mul_f32 v[12:13], v[16:17], s[0:1] op_sel_hi:[1,0]
	v_pk_mul_f32 v[6:7], v[14:15], s[0:1] op_sel_hi:[1,0]
	v_lshl_add_u64 v[4:5], s[94:95], 0, v[4:5]
	v_lshl_add_u64 v[14:15], v[4:5], 0, v[60:61]
	v_cvt_pk_bf16_f32 v4, v8, v9
	v_cvt_pk_bf16_f32 v5, v10, v11
	v_cvt_pk_bf16_f32 v6, v6, v7
	v_cvt_pk_bf16_f32 v7, v12, v13
	global_store_dwordx4 v[14:15], v[4:7], off offset:256
	s_branch .LBB0_45
